# row-sum MFMA 32x32x64 replaced by 16x16x128 with lane-masked ones operand in MLA/diff attention loops
# speedup vs baseline: 1.0136x; 1.0136x over previous
.LBB0_1288:
	s_ashr_i32 s8, s6, 6
	s_and_b32 s9, s6, 63
	s_lshr_b32 s6, s42, 1
	s_add_i32 s20, s6, s30
	s_lshl_b32 s6, s42, 5
	s_and_b32 s6, s6, 32
	s_add_i32 s26, s6, s29
	s_and_b64 s[6:7], s[14:15], exec
	s_cselect_b32 s8, s20, s8
	s_cselect_b32 s6, s26, s9
	s_lshr_b32 s7, s8, 3
	s_mulk_i32 s7, 0x4100
	s_lshl_b32 s6, s6, 8
	s_and_b32 s9, s8, 7
	s_add_i32 s7, s7, s6
	v_add_u32_e32 v166, s7, v170
	s_lshl_b32 s20, s9, 7
	s_lshl_b32 s6, s9, 2
	s_mul_i32 s44, s8, 0x208000
	v_ashrrev_i32_e32 v167, 31, v166
	s_mul_hi_i32 s45, s8, 0x208000
	s_add_u32 s53, s31, s44
	v_lshlrev_b64 v[4:5], 5, v[166:167]
	s_addc_u32 s55, s34, s45
	s_mul_i32 s50, s8, 0x104000
	v_lshl_add_u64 v[4:5], s[12:13], 0, v[4:5]
	s_mov_b32 s7, s21
	s_mul_hi_i32 s51, s8, 0x104000
	s_add_u32 s62, s35, s50
	v_lshl_add_u64 v[4:5], v[4:5], 0, s[6:7]
	s_addc_u32 s63, s36, s51
	s_add_i32 s6, s8, 32
	v_lshlrev_b64 v[2:3], 10, v[166:167]
	s_ashr_i32 s7, s6, 31
	v_lshl_add_u64 v[2:3], s[16:17], 0, v[2:3]
	s_lshl_b64 s[6:7], s[6:7], 2
	v_lshl_add_u64 v[2:3], v[2:3], 0, s[20:21]
	s_add_u32 s6, s3, s6
	s_addc_u32 s7, s28, s7
	v_lshl_add_u64 v[2:3], v[2:3], 0, v[178:179]
	global_load_dword v58, v[4:5], off
	global_load_dword v50, v163, s[6:7]
	global_load_dwordx4 v[142:145], v[2:3], off offset:16
	global_load_dwordx4 v[138:141], v[2:3], off
	global_load_dwordx4 v[150:153], v[2:3], off offset:80
	global_load_dwordx4 v[146:149], v[2:3], off offset:64
	v_readfirstlane_b32 s6, v1
	s_ashr_i32 s26, s6, 6
	s_cmp_lt_i32 s26, 6
	s_mul_i32 s46, s26, 0xc00
	s_cselect_b64 s[8:9], -1, 0
	s_add_i32 s52, s46, 0xffffc000
	s_add_u32 s27, s62, s52
	s_addc_u32 s43, s63, 0
	s_ashr_i32 s47, s46, 31
	s_add_u32 s49, s53, s46
	s_addc_u32 s64, s55, s47
	s_and_b64 s[6:7], s[8:9], exec
	s_cselect_b32 s7, s64, s43
	s_cselect_b32 s6, s49, s27
	s_add_i32 s43, s46, 0
	s_cmp_lt_i32 s26, 5
	s_cselect_b64 s[26:27], -1, 0
	s_add_i32 s65, s46, 0x400
	s_ashr_i32 s66, s65, 31
	s_add_u32 s67, s49, 0x400
	s_addc_u32 s68, s64, 0
	s_add_i32 s48, s46, 0xffffc400
	s_add_u32 s69, s62, s48
	s_addc_u32 s70, s63, 0
	v_lshl_add_u64 v[2:3], s[6:7], 0, v[164:165]
	s_and_b64 s[6:7], s[26:27], exec
	s_mov_b32 m0, s43
	s_cselect_b32 s7, s68, s70
	s_cselect_b32 s6, s67, s69
	s_add_i32 s67, s46, 0x800
	v_lshrrev_b32 v154, 2, v0
	v_xor_b32 v154, v154, v0
	v_bfe_u32 v154, v154, 2, 1
	v_add_u32 v154, -1, v154
	v_and_b32 v154, 0x38383838, v154
	v_mov_b32 v155, v154
	v_mov_b32 v156, v154
	v_mov_b32 v157, v154
	v_mov_b32 v158, v154
	v_mov_b32 v159, v154
	v_mov_b32 v160, v154
	v_mov_b32 v161, v154
	global_load_lds_dwordx4 v[2:3], off
	s_add_i32 m0, s43, 0x400
	s_ashr_i32 s68, s67, 31
	s_add_u32 s69, s49, 0x800
	s_addc_u32 s64, s64, 0
	s_add_i32 s49, s46, 0xffffc800
	s_add_u32 s70, s62, s49
	s_addc_u32 s71, s63, 0
	v_lshl_add_u64 v[2:3], s[6:7], 0, v[164:165]
	s_and_b64 s[6:7], s[26:27], exec
	global_load_lds_dwordx4 v[2:3], off
	s_cselect_b32 s7, s64, s71
	s_cselect_b32 s6, s69, s70
	s_add_i32 m0, s43, 0x800
	s_add_u32 s62, s62, 0x2000
	s_addc_u32 s63, s63, 0
	s_add_u32 s53, s53, 0x4000
	s_addc_u32 s55, s55, 0
	s_add_u32 s64, s53, s46
	s_addc_u32 s69, s55, s47
	s_add_u32 s70, s62, s52
	s_addc_u32 s71, s63, 0
	v_lshl_add_u64 v[2:3], s[6:7], 0, v[164:165]
	s_and_b64 s[6:7], s[8:9], exec
	global_load_lds_dwordx4 v[2:3], off
	s_cselect_b32 s7, s69, s71
	s_cselect_b32 s6, s64, s70
	s_add_i32 m0, s43, 0x6000
	s_add_u32 s64, s53, s65
	s_addc_u32 s65, s55, s66
	s_add_u32 s66, s62, s48
	s_addc_u32 s69, s63, 0
	v_lshl_add_u64 v[2:3], s[6:7], 0, v[164:165]
	s_and_b64 s[6:7], s[26:27], exec
	global_load_lds_dwordx4 v[2:3], off
	s_cselect_b32 s7, s65, s69
	s_cselect_b32 s6, s64, s66
	s_add_i32 m0, s43, 0x6400
	s_add_u32 s53, s53, s67
	s_addc_u32 s55, s55, s68
	s_add_u32 s62, s62, s49
	s_addc_u32 s63, s63, 0
	v_lshl_add_u64 v[2:3], s[6:7], 0, v[164:165]
	s_and_b64 s[6:7], s[26:27], exec
	s_cselect_b32 s7, s55, s63
	s_cselect_b32 s6, s53, s62
	global_load_lds_dwordx4 v[2:3], off
	v_lshl_add_u64 v[2:3], s[6:7], 0, v[164:165]
	s_add_i32 m0, s43, 0x6800
	s_waitcnt vmcnt(0)
	v_mul_f32_e32 v51, 0x4f800000, v50
	global_load_lds_dwordx4 v[2:3], off
	s_waitcnt vmcnt(3)
	s_barrier
	ds_read_b128 v[2:5], v171
	ds_read_b128 v[6:9], v171 offset:1024
	s_waitcnt lgkmcnt(0)
	v_mfma_scale_f32_32x32x64_f8f6f4 v[2:17], v[2:9], v[138:145], 0, v174, v174 op_sel_hi:[0,0,0]
	ds_read_b128 v[18:21], v171 offset:2048
	ds_read_b128 v[22:25], v171 offset:3072
	v_cmp_gt_f32_e32 vcc, s37, v50
	s_add_u32 s44, s44, s46
	s_addc_u32 s45, s45, s47
	v_cndmask_b32_e32 v59, v50, v51, vcc
	v_sqrt_f32_e32 v60, v59
	s_add_u32 s46, s50, s49
	s_addc_u32 s47, s51, 0
	s_add_u32 s48, s50, s48
	v_add_u32_e32 v61, -1, v60
	v_fma_f32 v62, -v61, v60, v59
	v_cmp_ge_f32_e64 s[6:7], 0, v62
	v_add_u32_e32 v62, 1, v60
	s_addc_u32 s49, s51, 0
	v_cndmask_b32_e64 v61, v60, v61, s[6:7]
	s_waitcnt lgkmcnt(0)
	v_mfma_scale_f32_32x32x64_f8f6f4 v[2:17], v[18:25], v[146:153], v[2:17], v174, v174 op_sel_hi:[0,0,0]
	ds_read_b128 v[18:21], v171 offset:4096
	ds_read_b128 v[22:25], v171 offset:5120
	ds_read_b128 v[34:37], v171 offset:6144
	ds_read_b128 v[38:41], v171 offset:7168
	v_fma_f32 v60, -v62, v60, v59
	v_cmp_lt_f32_e64 s[6:7], 0, v60
	s_add_u32 s50, s50, s52
	s_addc_u32 s51, s51, 0
	v_cndmask_b32_e64 v60, v61, v62, s[6:7]
	s_mov_b32 s55, 0
	s_mov_b32 s52, 0
	v_mov_b32_e32 v61, v163
	v_mov_b32_e32 v62, v163
	v_mov_b32_e32 v63, v163
	v_mov_b32_e32 v64, v163
	v_mov_b32_e32 v65, v163
	s_nop 3
	v_max3_f32 v2, v2, s39, v3
	s_waitcnt lgkmcnt(0)
	v_mfma_scale_f32_32x32x64_f8f6f4 v[18:33], v[18:25], v[138:145], 0, v174, v174 op_sel_hi:[0,0,0]
	v_max3_f32 v2, v2, v4, v5
	v_max3_f32 v2, v2, v6, v7
	v_max3_f32 v2, v2, v8, v9
	v_max3_f32 v2, v2, v10, v11
	v_max3_f32 v2, v2, v12, v13
	v_max3_f32 v2, v2, v14, v15
	v_max3_f32 v2, v2, v16, v17
	v_mfma_scale_f32_32x32x64_f8f6f4 v[18:33], v[34:41], v[146:153], v[18:33], v174, v174 op_sel_hi:[0,0,0]
	ds_read_b128 v[34:37], v171 offset:8192
	ds_read_b128 v[38:41], v171 offset:9216
	ds_read_b128 v[50:53], v171 offset:10240
	ds_read_b128 v[54:57], v171 offset:11264
	s_waitcnt lgkmcnt(0)
	v_mfma_scale_f32_32x32x64_f8f6f4 v[34:49], v[34:41], v[138:145], 0, v174, v174 op_sel_hi:[0,0,0]
	s_nop 13
	v_max3_f32 v2, v2, v18, v19
	v_max3_f32 v2, v2, v20, v21
	v_max3_f32 v18, v2, v22, v23
	v_max3_f32 v18, v18, v24, v25
	v_max3_f32 v18, v18, v26, v27
	v_max3_f32 v18, v18, v28, v29
	v_max3_f32 v18, v18, v30, v31
	v_max3_f32 v26, v18, v32, v33
	v_mov_b32_e32 v27, v163
	v_mov_b32_e32 v28, v163
	v_mov_b32_e32 v29, v163
	v_mov_b32_e32 v30, v163
	v_mov_b32_e32 v31, v163
	v_mov_b32_e32 v32, v163
	v_mov_b32_e32 v33, v163
	v_mfma_scale_f32_32x32x64_f8f6f4 v[34:49], v[50:57], v[146:153], v[34:49], v174, v174 op_sel_hi:[0,0,0]
	v_mul_f32_e32 v50, 0x37800000, v60
	v_cndmask_b32_e32 v60, v60, v50, vcc
	ds_read_b128 v[50:53], v171 offset:12288
	ds_read_b128 v[54:57], v171 offset:13312
	ds_read_b128 v[18:21], v171 offset:14336
	ds_read_b128 v[22:25], v171 offset:15360
	v_cmp_lt_i32_e32 vcc, v176, v177
	s_nop 12
	v_max3_f32 v26, v26, v34, v35
	s_waitcnt lgkmcnt(0)
	v_mfma_scale_f32_32x32x64_f8f6f4 v[2:17], v[50:57], v[138:145], 0, v174, v174 op_sel_hi:[0,0,0]
	v_max3_f32 v26, v26, v36, v37
	v_max3_f32 v26, v26, v38, v39
	v_max3_f32 v26, v26, v40, v41
	v_max3_f32 v26, v26, v42, v43
	v_max3_f32 v26, v26, v44, v45
	v_max3_f32 v26, v26, v46, v47
	v_max3_f32 v26, v26, v48, v49
	v_mov_b32_e32 v50, 0
	v_mov_b32_e32 v51, v163
	v_mov_b32_e32 v52, v163
	v_mov_b32_e32 v53, v163
	v_mov_b32_e32 v54, v163
	v_mov_b32_e32 v55, v163
	v_mov_b32_e32 v56, v163
	v_mov_b32_e32 v57, v163
	v_mfma_scale_f32_32x32x64_f8f6f4 v[2:17], v[18:25], v[146:153], v[2:17], v174, v174 op_sel_hi:[0,0,0]
	v_mov_b32_e32 v18, 0
	v_mov_b32_e32 v19, v163
	v_mov_b32_e32 v20, v163
	v_mov_b32_e32 v21, v163
	v_mov_b32_e32 v22, v163
	v_mov_b32_e32 v23, v163
	v_mov_b32_e32 v24, v163
	v_mov_b32_e32 v25, v163
	s_nop 11
	v_max3_f32 v2, v26, v2, v3
	v_max3_f32 v2, v2, v4, v5
	v_max3_f32 v2, v2, v6, v7
	v_max3_f32 v2, v2, v8, v9
	v_max3_f32 v2, v2, v10, v11
	v_max3_f32 v2, v2, v12, v13
	v_max3_f32 v2, v2, v14, v15
	v_cndmask_b32_e32 v3, v175, v176, vcc
	v_max3_f32 v2, v2, v16, v17
	v_lshlrev_b32_e32 v3, 2, v3
	ds_bpermute_b32 v3, v3, v2
	v_cmp_class_f32_e32 vcc, v59, v172
	v_mov_b32_e32 v26, v163
	v_mov_b32_e32 v5, v163
	v_cndmask_b32_e32 v4, v60, v59, vcc
	s_waitcnt lgkmcnt(0)
	v_max_f32_e32 v3, v3, v3
	v_mul_f32_e32 v4, v58, v4
	v_max_f32_e32 v2, v2, v3
	v_fmamk_f32 v4, v4, 0x3f90a3d7, v173
	v_add_f32_e32 v2, 0x42800000, v2
	v_min_f32_e32 v2, v4, v2
	v_add_f32_e32 v2, 0xc2ec0000, v2
	v_xor_b32_e32 v34, 0x80000000, v2
	v_mov_b32_e32 v35, v34
	v_mov_b32_e32 v36, v34
	v_mov_b32_e32 v37, v34
	v_mov_b32_e32 v38, v34
	v_mov_b32_e32 v39, v34
	v_mov_b32_e32 v40, v34
	v_mov_b32_e32 v41, v34
	v_mov_b32_e32 v42, v34
	v_mov_b32_e32 v43, v34
	v_mov_b32_e32 v44, v34
	v_mov_b32_e32 v45, v34
	v_mov_b32_e32 v46, v34
	v_mov_b32_e32 v47, v34
	v_mov_b32_e32 v48, v34
	v_mov_b32_e32 v49, v34
	v_mov_b32_e32 v58, v163
	v_mov_b32_e32 v59, v163
	v_mov_b32_e32 v60, v163
	v_mov_b32_e32 v2, 0
	v_mov_b32_e32 v3, v163
	v_mov_b32_e32 v4, v163
	v_mov_b32_e32 v6, v163
	v_mov_b32_e32 v7, v163
	v_mov_b32_e32 v8, v163
	v_mov_b32_e32 v9, v163
	v_mov_b32_e32 v10, v163
	v_mov_b32_e32 v11, v163
	v_mov_b32_e32 v12, v163
	v_mov_b32_e32 v13, v163
	v_mov_b32_e32 v14, v163
	v_mov_b32_e32 v15, v163
	v_mov_b32_e32 v16, v163
	v_mov_b32_e32 v17, v163
	s_branch .LBB0_1290
.LBB0_1289:
	s_mulk_i32 s55, 0x6000
	v_add_u32_e32 v167, s55, v171
	ds_read_b128 v[82:85], v167
	ds_read_b128 v[86:89], v167 offset:1024
	ds_read_b128 v[66:69], v167 offset:4096
	ds_read_b128 v[70:73], v167 offset:5120
	ds_read_b128 v[90:93], v167 offset:2048
	ds_read_b128 v[94:97], v167 offset:3072
	ds_read_b128 v[98:101], v167 offset:6144
	ds_read_b128 v[102:105], v167 offset:7168
	ds_read_b128 v[190:193], v167 offset:16384
	ds_read_b128 v[194:197], v167 offset:17408
	ds_read_b128 v[198:201], v167 offset:18432
	ds_read_b128 v[202:205], v167 offset:19456
	s_waitcnt lgkmcnt(0)
	v_mfma_scale_f32_32x32x64_f8f6f4 v[66:81], v[66:73], v[138:145], v[34:49], v174, v174 op_sel_hi:[0,0,0]
	s_add_i32 s52, s52, 2
	s_add_u32 s44, s44, 0x8000
	s_addc_u32 s45, s45, 0
	s_add_u32 s46, s46, 0x4000
	s_addc_u32 s47, s47, 0
	s_add_u32 s48, s48, 0x4000
	s_addc_u32 s49, s49, 0
	s_add_u32 s50, s50, 0x4000
	s_addc_u32 s51, s51, 0
	s_andn2_b64 vcc, exec, s[6:7]
	s_mov_b32 s55, s53
	v_mfma_scale_f32_32x32x64_f8f6f4 v[122:137], v[82:89], v[138:145], v[34:49], v174, v174 op_sel_hi:[0,0,0]
	v_mfma_scale_f32_32x32x64_f8f6f4 v[66:81], v[98:105], v[146:153], v[66:81], v174, v174 op_sel_hi:[0,0,0]
	ds_read_b128 v[82:85], v167 offset:12288
	ds_read_b128 v[86:89], v167 offset:13312
	ds_read_b128 v[98:101], v167 offset:8192
	ds_read_b128 v[102:105], v167 offset:9216
	ds_read_b128 v[206:209], v167 offset:10240
	ds_read_b128 v[210:213], v167 offset:11264
	ds_read_b128 v[106:109], v167 offset:14336
	ds_read_b128 v[110:113], v167 offset:15360
	s_nop 11
	v_med3_f32 v66, v66, 0, v180
	v_mfma_scale_f32_32x32x64_f8f6f4 v[122:137], v[90:97], v[146:153], v[122:137], v174, v174 op_sel_hi:[0,0,0]
	v_med3_f32 v67, v67, 0, v180
	v_cvt_pk_u8_f32 v66, v66, 0, 0
	v_med3_f32 v68, v68, 0, v180
	v_cvt_pk_u8_f32 v66, v67, 1, v66
	v_med3_f32 v69, v69, 0, v180
	v_cvt_pk_u8_f32 v66, v68, 2, v66
	v_med3_f32 v68, v71, 0, v180
	v_med3_f32 v67, v72, 0, v180
	s_waitcnt lgkmcnt(0)
	v_mfma_scale_f32_32x32x64_f8f6f4 v[82:97], v[82:89], v[138:145], v[34:49], v174, v174 op_sel_hi:[0,0,0]
	v_mfma_scale_f32_32x32x64_f8f6f4 v[82:97], v[106:113], v[146:153], v[82:97], v174, v174 op_sel_hi:[0,0,0]
	v_mfma_scale_f32_32x32x64_f8f6f4 v[106:121], v[98:105], v[138:145], v[34:49], v174, v174 op_sel_hi:[0,0,0]
	s_nop 7
	v_med3_f32 v101, v122, 0, v180
	v_med3_f32 v100, v123, 0, v180
	v_cvt_pk_u8_f32 v101, v101, 0, 0
	v_med3_f32 v99, v124, 0, v180
	v_cvt_pk_u8_f32 v100, v100, 1, v101
	v_med3_f32 v101, v126, 0, v180
	v_cvt_pk_u8_f32 v126, v69, 3, v66
	v_med3_f32 v69, v70, 0, v180
	v_med3_f32 v98, v125, 0, v180
	v_cvt_pk_u8_f32 v99, v99, 2, v100
	v_med3_f32 v100, v127, 0, v180
	v_cvt_pk_u8_f32 v101, v101, 0, 0
	v_cvt_pk_u8_f32 v69, v69, 0, 0
	v_cvt_pk_u8_f32 v122, v98, 3, v99
	v_med3_f32 v99, v128, 0, v180
	v_cvt_pk_u8_f32 v100, v100, 1, v101
	v_med3_f32 v101, v130, 0, v180
	v_cvt_pk_u8_f32 v68, v68, 1, v69
	v_med3_f32 v69, v74, 0, v180
	v_med3_f32 v98, v129, 0, v180
	v_cvt_pk_u8_f32 v99, v99, 2, v100
	v_med3_f32 v100, v131, 0, v180
	v_cvt_pk_u8_f32 v101, v101, 0, 0
	v_med3_f32 v66, v73, 0, v180
	v_cvt_pk_u8_f32 v67, v67, 2, v68
	v_med3_f32 v68, v75, 0, v180
	v_cvt_pk_u8_f32 v69, v69, 0, 0
	v_cvt_pk_u8_f32 v123, v98, 3, v99
	v_med3_f32 v99, v132, 0, v180
	v_cvt_pk_u8_f32 v100, v100, 1, v101
	v_med3_f32 v101, v134, 0, v180
	v_cvt_pk_u8_f32 v127, v66, 3, v67
	v_med3_f32 v67, v76, 0, v180
	v_cvt_pk_u8_f32 v68, v68, 1, v69
	v_med3_f32 v69, v78, 0, v180
	v_med3_f32 v98, v133, 0, v180
	v_cvt_pk_u8_f32 v99, v99, 2, v100
	v_med3_f32 v100, v135, 0, v180
	v_cvt_pk_u8_f32 v101, v101, 0, 0
	v_med3_f32 v66, v77, 0, v180
	v_cvt_pk_u8_f32 v67, v67, 2, v68
	v_med3_f32 v68, v79, 0, v180
	v_cvt_pk_u8_f32 v69, v69, 0, 0
	v_cvt_pk_u8_f32 v124, v98, 3, v99
	v_med3_f32 v99, v136, 0, v180
	v_cvt_pk_u8_f32 v100, v100, 1, v101
	v_cvt_pk_u8_f32 v128, v66, 3, v67
	v_med3_f32 v67, v80, 0, v180
	v_cvt_pk_u8_f32 v68, v68, 1, v69
	v_mfma_scale_f32_32x32x64_f8f6f4 v[106:121], v[206:213], v[146:153], v[106:121], v174, v174 op_sel_hi:[0,0,0]
	v_med3_f32 v98, v137, 0, v180
	v_cvt_pk_u8_f32 v99, v99, 2, v100
	v_med3_f32 v66, v81, 0, v180
	v_cvt_pk_u8_f32 v67, v67, 2, v68
	v_cvt_pk_u8_f32 v125, v98, 3, v99
	v_cvt_pk_u8_f32 v129, v66, 3, v67
	v_med3_f32 v82, v82, 0, v180
	v_med3_f32 v83, v83, 0, v180
	v_cvt_pk_u8_f32 v82, v82, 0, 0
	v_med3_f32 v84, v84, 0, v180
	v_cvt_pk_u8_f32 v82, v83, 1, v82
	v_med3_f32 v85, v85, 0, v180
	v_cvt_pk_u8_f32 v82, v84, 2, v82
	v_med3_f32 v84, v87, 0, v180
	v_med3_f32 v83, v88, 0, v180
	v_mfma_scale_f32_32x32x64_f8f6f4 v[18:33], v[190:197], v[122:129], v[18:33], v174, v174 op_sel_hi:[0,0,0] blgp:1
	s_nop 3
	v_med3_f32 v106, v106, 0, v180
	v_med3_f32 v107, v107, 0, v180
	v_cvt_pk_u8_f32 v106, v106, 0, 0
	v_med3_f32 v108, v108, 0, v180
	v_cvt_pk_u8_f32 v106, v107, 1, v106
	v_med3_f32 v109, v109, 0, v180
	v_cvt_pk_u8_f32 v106, v108, 2, v106
	v_med3_f32 v108, v111, 0, v180
	v_med3_f32 v107, v112, 0, v180
	v_med3_f32 v114, v114, 0, v180
	v_med3_f32 v115, v115, 0, v180
	v_cvt_pk_u8_f32 v114, v114, 0, 0
	v_med3_f32 v116, v116, 0, v180
	v_cvt_pk_u8_f32 v114, v115, 1, v114
	v_med3_f32 v117, v117, 0, v180
	v_mfma_scale_f32_32x32x64_f8f6f4 v[2:17], v[198:205], v[122:129], v[2:17], v174, v174 op_sel_hi:[0,0,0] blgp:1
	ds_read_b128 v[190:193], v167 offset:20480
	ds_read_b128 v[194:197], v167 offset:21504
	ds_read_b128 v[198:201], v167 offset:22528
	ds_read_b128 v[202:205], v167 offset:23552
	ds_read_b128 v[66:69], v167 offset:28672
	ds_read_b128 v[70:73], v167 offset:29696
	ds_read_b128 v[98:101], v167 offset:24576
	ds_read_b128 v[102:105], v167 offset:25600
	ds_read_b128 v[206:209], v167 offset:26624
	ds_read_b128 v[210:213], v167 offset:27648
	ds_read_b128 v[130:133], v167 offset:30720
	ds_read_b128 v[134:137], v167 offset:31744
	v_cvt_pk_u8_f32 v114, v116, 2, v114
	v_med3_f32 v116, v119, 0, v180
	v_med3_f32 v115, v120, 0, v180
	s_waitcnt lgkmcnt(0)
	v_mfma_scale_f32_32x32x64_f8f6f4 v[66:81], v[66:73], v[138:145], v[34:49], v174, v174 op_sel_hi:[0,0,0]
	v_mfma_scale_f32_32x32x64_f8f6f4 v[66:81], v[130:137], v[146:153], v[66:81], v174, v174 op_sel_hi:[0,0,0]
	v_cvt_pk_u8_f32 v130, v109, 3, v106
	v_med3_f32 v109, v110, 0, v180
	v_cvt_pk_u8_f32 v109, v109, 0, 0
	v_cvt_pk_u8_f32 v108, v108, 1, v109
	v_med3_f32 v106, v113, 0, v180
	v_cvt_pk_u8_f32 v107, v107, 2, v108
	v_cvt_pk_u8_f32 v131, v106, 3, v107
	v_cvt_pk_u8_f32 v134, v85, 3, v82
	v_med3_f32 v85, v86, 0, v180
	v_cvt_pk_u8_f32 v85, v85, 0, 0
	v_cvt_pk_u8_f32 v84, v84, 1, v85
	v_med3_f32 v85, v90, 0, v180
	v_med3_f32 v82, v89, 0, v180
	v_cvt_pk_u8_f32 v83, v83, 2, v84
	v_med3_f32 v84, v91, 0, v180
	v_mfma_scale_f32_32x32x64_f8f6f4 v[98:113], v[98:105], v[138:145], v[34:49], v174, v174 op_sel_hi:[0,0,0]
	v_cvt_pk_u8_f32 v85, v85, 0, 0
	v_cvt_pk_u8_f32 v132, v117, 3, v114
	v_med3_f32 v117, v118, 0, v180
	v_cvt_pk_u8_f32 v135, v82, 3, v83
	v_med3_f32 v83, v92, 0, v180
	v_cvt_pk_u8_f32 v84, v84, 1, v85
	v_med3_f32 v85, v94, 0, v180
	v_cvt_pk_u8_f32 v117, v117, 0, 0
	v_med3_f32 v82, v93, 0, v180
	v_cvt_pk_u8_f32 v83, v83, 2, v84
	v_med3_f32 v84, v95, 0, v180
	v_cvt_pk_u8_f32 v85, v85, 0, 0
	v_cvt_pk_u8_f32 v116, v116, 1, v117
	v_cvt_pk_u8_f32 v136, v82, 3, v83
	v_med3_f32 v83, v96, 0, v180
	v_cvt_pk_u8_f32 v84, v84, 1, v85
	v_med3_f32 v114, v121, 0, v180
	v_cvt_pk_u8_f32 v115, v115, 2, v116
	v_med3_f32 v82, v97, 0, v180
	v_cvt_pk_u8_f32 v83, v83, 2, v84
	v_cvt_pk_u8_f32 v133, v114, 3, v115
	v_cvt_pk_u8_f32 v137, v82, 3, v83
	v_mfma_scale_f32_32x32x64_f8f6f4 v[98:113], v[206:213], v[146:153], v[98:113], v174, v174 op_sel_hi:[0,0,0]
	v_med3_f32 v66, v66, 0, v180
	v_med3_f32 v67, v67, 0, v180
	v_cvt_pk_u8_f32 v66, v66, 0, 0
	v_med3_f32 v68, v68, 0, v180
	v_cvt_pk_u8_f32 v66, v67, 1, v66
	v_med3_f32 v69, v69, 0, v180
	v_cvt_pk_u8_f32 v66, v68, 2, v66
	v_med3_f32 v68, v71, 0, v180
	v_med3_f32 v67, v72, 0, v180
	s_nop 10
	v_med3_f32 v98, v98, 0, v180
	v_mfma_scale_f32_16x16x128_f8f6f4 v[50:53], v[154:161], v[122:129], v[50:53], v174, v174 op_sel_hi:[0,0,0] blgp:1
	v_med3_f32 v99, v99, 0, v180
	v_cvt_pk_u8_f32 v98, v98, 0, 0
	v_med3_f32 v100, v100, 0, v180
	v_cvt_pk_u8_f32 v98, v99, 1, v98
	v_med3_f32 v101, v101, 0, v180
	v_cvt_pk_u8_f32 v98, v100, 2, v98
	v_med3_f32 v102, v102, 0, v180
	v_cvt_pk_u8_f32 v98, v101, 3, v98
	v_med3_f32 v101, v103, 0, v180
	v_cvt_pk_u8_f32 v102, v102, 0, 0
	v_med3_f32 v103, v106, 0, v180
	v_med3_f32 v100, v104, 0, v180
	v_cvt_pk_u8_f32 v101, v101, 1, v102
	v_med3_f32 v102, v107, 0, v180
	v_cvt_pk_u8_f32 v103, v103, 0, 0
	v_mfma_scale_f32_32x32x64_f8f6f4 v[18:33], v[190:197], v[130:137], v[18:33], v174, v174 op_sel_hi:[0,0,0] blgp:1
	v_med3_f32 v104, v110, 0, v180
	v_med3_f32 v99, v105, 0, v180
	v_cvt_pk_u8_f32 v100, v100, 2, v101
	v_med3_f32 v101, v108, 0, v180
	v_cvt_pk_u8_f32 v102, v102, 1, v103
	v_med3_f32 v103, v111, 0, v180
	v_cvt_pk_u8_f32 v104, v104, 0, 0
	v_cvt_pk_u8_f32 v99, v99, 3, v100
	v_med3_f32 v100, v109, 0, v180
	v_cvt_pk_u8_f32 v101, v101, 2, v102
	v_med3_f32 v102, v112, 0, v180
	v_cvt_pk_u8_f32 v103, v103, 1, v104
	v_cvt_pk_u8_f32 v100, v100, 3, v101
	v_med3_f32 v101, v113, 0, v180
	v_cvt_pk_u8_f32 v102, v102, 2, v103
	v_mfma_scale_f32_32x32x64_f8f6f4 v[2:17], v[198:205], v[130:137], v[2:17], v174, v174 op_sel_hi:[0,0,0] blgp:1
	ds_read_b128 v[114:117], v167 offset:32768
	ds_read_b128 v[118:121], v167 offset:33792
	ds_read_b128 v[82:85], v167 offset:36864
	ds_read_b128 v[86:89], v167 offset:37888
	ds_read_b128 v[190:193], v167 offset:34816
	ds_read_b128 v[194:197], v167 offset:35840
	ds_read_b128 v[122:125], v167 offset:38912
	ds_read_b128 v[126:129], v167 offset:39936
	ds_read_b128 v[198:201], v167 offset:40960
	ds_read_b128 v[202:205], v167 offset:41984
	ds_read_b128 v[206:209], v167 offset:43008
	ds_read_b128 v[210:213], v167 offset:44032
	v_cvt_pk_u8_f32 v101, v101, 3, v102
	v_cvt_pk_u8_f32 v102, v69, 3, v66
	v_med3_f32 v69, v70, 0, v180
	v_cvt_pk_u8_f32 v69, v69, 0, 0
	v_cvt_pk_u8_f32 v68, v68, 1, v69
	v_med3_f32 v69, v74, 0, v180
	v_med3_f32 v66, v73, 0, v180
	v_cvt_pk_u8_f32 v67, v67, 2, v68
	v_med3_f32 v68, v75, 0, v180
	v_cvt_pk_u8_f32 v69, v69, 0, 0
	v_cvt_pk_u8_f32 v103, v66, 3, v67
	v_med3_f32 v67, v76, 0, v180
	v_cvt_pk_u8_f32 v68, v68, 1, v69
	s_waitcnt lgkmcnt(0)
	v_mfma_scale_f32_32x32x64_f8f6f4 v[82:97], v[82:89], v[138:145], v[34:49], v174, v174 op_sel_hi:[0,0,0]
	v_med3_f32 v69, v78, 0, v180
	v_med3_f32 v66, v77, 0, v180
	v_cvt_pk_u8_f32 v67, v67, 2, v68
	v_med3_f32 v68, v79, 0, v180
	v_cvt_pk_u8_f32 v69, v69, 0, 0
	v_cvt_pk_u8_f32 v104, v66, 3, v67
	v_med3_f32 v67, v80, 0, v180
	v_cvt_pk_u8_f32 v68, v68, 1, v69
	v_med3_f32 v66, v81, 0, v180
	v_cvt_pk_u8_f32 v67, v67, 2, v68
	v_cvt_pk_u8_f32 v105, v66, 3, v67
	v_mfma_scale_f32_32x32x64_f8f6f4 v[82:97], v[122:129], v[146:153], v[82:97], v174, v174 op_sel_hi:[0,0,0]
	v_mfma_scale_f32_32x32x64_f8f6f4 v[114:129], v[114:121], v[138:145], v[34:49], v174, v174 op_sel_hi:[0,0,0]
	s_nop 15
	s_nop 2
	v_med3_f32 v81, v82, 0, v180
	v_cvt_pk_u8_f32 v81, v81, 0, 0
	v_med3_f32 v82, v86, 0, v180
	v_cvt_pk_u8_f32 v82, v82, 0, 0
	ds_read_b128 v[66:69], v167 offset:45056
	ds_read_b128 v[70:73], v167 offset:46080
	v_mfma_scale_f32_32x32x64_f8f6f4 v[114:129], v[190:197], v[146:153], v[114:129], v174, v174 op_sel_hi:[0,0,0]
	v_mfma_scale_f32_16x16x128_f8f6f4 v[50:53], v[154:161], v[130:137], v[50:53], v174, v174 op_sel_hi:[0,0,0] blgp:1
	s_nop 15
	s_nop 2
	v_med3_f32 v77, v114, 0, v180
	v_med3_f32 v76, v115, 0, v180
	v_cvt_pk_u8_f32 v77, v77, 0, 0
	v_med3_f32 v78, v118, 0, v180
	v_med3_f32 v75, v116, 0, v180
	v_cvt_pk_u8_f32 v76, v76, 1, v77
	v_med3_f32 v77, v119, 0, v180
	v_cvt_pk_u8_f32 v78, v78, 0, 0
	v_med3_f32 v79, v122, 0, v180
	v_med3_f32 v74, v117, 0, v180
	v_cvt_pk_u8_f32 v75, v75, 2, v76
	v_med3_f32 v76, v120, 0, v180
	v_cvt_pk_u8_f32 v77, v77, 1, v78
	v_med3_f32 v78, v123, 0, v180
	v_cvt_pk_u8_f32 v79, v79, 0, 0
	v_mfma_scale_f32_32x32x64_f8f6f4 v[18:33], v[198:205], v[98:105], v[18:33], v174, v174 op_sel_hi:[0,0,0] blgp:1
	v_med3_f32 v80, v126, 0, v180
	v_cvt_pk_u8_f32 v74, v74, 3, v75
	v_med3_f32 v75, v121, 0, v180
	v_cvt_pk_u8_f32 v76, v76, 2, v77
	v_med3_f32 v77, v124, 0, v180
	v_cvt_pk_u8_f32 v78, v78, 1, v79
	v_med3_f32 v79, v127, 0, v180
	v_cvt_pk_u8_f32 v80, v80, 0, 0
	v_cvt_pk_u8_f32 v75, v75, 3, v76
	v_med3_f32 v76, v125, 0, v180
	v_cvt_pk_u8_f32 v77, v77, 2, v78
	v_med3_f32 v78, v128, 0, v180
	v_cvt_pk_u8_f32 v79, v79, 1, v80
	v_med3_f32 v80, v83, 0, v180
	v_cvt_pk_u8_f32 v76, v76, 3, v77
	v_mfma_scale_f32_32x32x64_f8f6f4 v[2:17], v[206:213], v[98:105], v[2:17], v174, v174 op_sel_hi:[0,0,0] blgp:1
	v_med3_f32 v77, v129, 0, v180
	v_cvt_pk_u8_f32 v78, v78, 2, v79
	v_med3_f32 v79, v84, 0, v180
	v_cvt_pk_u8_f32 v80, v80, 1, v81
	v_med3_f32 v81, v87, 0, v180
	v_med3_f32 v83, v90, 0, v180
	v_cvt_pk_u8_f32 v77, v77, 3, v78
	v_med3_f32 v78, v85, 0, v180
	v_cvt_pk_u8_f32 v79, v79, 2, v80
	v_med3_f32 v80, v88, 0, v180
	v_cvt_pk_u8_f32 v81, v81, 1, v82
	v_med3_f32 v82, v91, 0, v180
	v_cvt_pk_u8_f32 v83, v83, 0, 0
	v_med3_f32 v84, v94, 0, v180
	v_cvt_pk_u8_f32 v78, v78, 3, v79
	v_mfma_scale_f32_16x16x128_f8f6f4 v[50:53], v[154:161], v[98:105], v[50:53], v174, v174 op_sel_hi:[0,0,0] blgp:1
	v_med3_f32 v79, v89, 0, v180
	v_cvt_pk_u8_f32 v80, v80, 2, v81
	v_med3_f32 v81, v92, 0, v180
	v_cvt_pk_u8_f32 v82, v82, 1, v83
	v_med3_f32 v83, v95, 0, v180
	v_cvt_pk_u8_f32 v84, v84, 0, 0
	v_cvt_pk_u8_f32 v79, v79, 3, v80
	v_med3_f32 v80, v93, 0, v180
	v_cvt_pk_u8_f32 v81, v81, 2, v82
	v_med3_f32 v82, v96, 0, v180
	v_cvt_pk_u8_f32 v83, v83, 1, v84
	v_cvt_pk_u8_f32 v80, v80, 3, v81
	v_med3_f32 v81, v97, 0, v180
	v_cvt_pk_u8_f32 v82, v82, 2, v83
	v_cvt_pk_u8_f32 v81, v81, 3, v82
	s_waitcnt lgkmcnt(0)
	s_nop 0
	v_mfma_scale_f32_32x32x64_f8f6f4 v[18:33], v[66:73], v[74:81], v[18:33], v174, v174 op_sel_hi:[0,0,0] blgp:1
	ds_read_b128 v[66:69], v167 offset:47104
	ds_read_b128 v[70:73], v167 offset:48128
	s_waitcnt lgkmcnt(0)
	v_mfma_scale_f32_32x32x64_f8f6f4 v[2:17], v[66:73], v[74:81], v[2:17], v174, v174 op_sel_hi:[0,0,0] blgp:1
	v_mfma_scale_f32_16x16x128_f8f6f4 v[50:53], v[154:161], v[74:81], v[50:53], v174, v174 op_sel_hi:[0,0,0] blgp:1
	s_cbranch_vccz .LBB0_1287

.LBB0_1298:
	s_ashr_i32 s10, s8, 6
	s_and_b32 s11, s8, 63
	s_lshr_b32 s8, s42, 1
	s_add_i32 s22, s8, s34
	s_lshl_b32 s8, s42, 5
	s_and_b32 s8, s8, 32
	s_add_i32 s26, s8, s31
	s_and_b64 s[8:9], s[16:17], exec
	s_cselect_b32 s9, s22, s10
	s_cselect_b32 s8, s26, s11
	s_ashr_i32 s10, s9, 3
	s_mul_i32 s11, s10, 0x4100
	s_lshl_b32 s8, s8, 8
	s_add_i32 s11, s11, s8
	v_add_u32_e32 v166, s11, v170
	v_ashrrev_i32_e32 v167, 31, v166
	s_and_b32 s43, s9, 7
	v_lshlrev_b64 v[2:3], 9, v[166:167]
	v_lshl_add_u64 v[2:3], s[18:19], 0, v[2:3]
	s_lshl_b32 s22, s43, 6
	v_lshl_add_u64 v[2:3], v[2:3], 0, s[22:23]
	s_lshl_b32 s22, s43, 2
	s_mul_i32 s44, s9, 0x104000
	s_mul_hi_i32 s45, s9, 0x104000
	s_add_u32 s53, s35, s44
	s_addc_u32 s55, s36, s45
	s_lshl_b32 s8, s10, 2
	s_bfe_u32 s10, s9, 0x20001
	s_or_b32 s50, s8, s10
	s_mul_hi_i32 s51, s50, 0x208000
	s_mul_i32 s50, s50, 0x208000
	s_add_u32 s62, s37, s50
	s_addc_u32 s63, s38, s51
	s_add_i32 s8, s9, 16
	s_ashr_i32 s9, s8, 31
	v_lshlrev_b64 v[4:5], 5, v[166:167]
	s_lshl_b64 s[8:9], s[8:9], 2
	v_lshl_add_u64 v[4:5], s[12:13], 0, v[4:5]
	s_add_u32 s8, s3, s8
	v_lshl_add_u64 v[4:5], v[4:5], 0, s[22:23]
	s_addc_u32 s9, s28, s9
	global_load_dword v42, v[4:5], off
	global_load_dword v18, v163, s[8:9]
	v_lshl_add_u64 v[2:3], v[2:3], 0, v[210:211]
	global_load_dwordx4 v[150:153], v[2:3], off offset:16
	global_load_dwordx4 v[146:149], v[2:3], off
	v_readfirstlane_b32 s8, v1
	s_ashr_i32 s26, s8, 6
	s_cmp_lt_i32 s26, 3
	s_mul_i32 s46, s26, 0xc00
	s_cselect_b64 s[10:11], -1, 0
	s_add_i32 s52, s46, 0xffffe000
	s_add_u32 s22, s62, s52
	s_addc_u32 s27, s63, 0
	s_ashr_i32 s47, s46, 31
	s_add_u32 s49, s53, s46
	s_addc_u32 s64, s55, s47
	s_and_b64 s[8:9], s[10:11], exec
	s_cselect_b32 s9, s64, s27
	s_cselect_b32 s8, s49, s22
	s_add_i32 s65, s46, 0x400
	s_add_i32 s22, s46, 0
	s_ashr_i32 s66, s65, 31
	s_add_u32 s27, s49, 0x400
	s_addc_u32 s67, s64, 0
	s_add_i32 s48, s46, 0xffffe400
	s_add_u32 s68, s62, s48
	s_addc_u32 s69, s63, 0
	v_lshl_add_u64 v[2:3], s[8:9], 0, v[164:165]
	s_mov_b32 m0, s22
	s_and_b64 s[8:9], s[10:11], exec
	v_lshrrev_b32 v154, 2, v0
	v_xor_b32 v154, v154, v0
	v_bfe_u32 v154, v154, 2, 1
	v_add_u32 v154, -1, v154
	v_and_b32 v154, 0x38383838, v154
	v_mov_b32 v155, v154
	v_mov_b32 v156, v154
	v_mov_b32 v157, v154
	v_mov_b32 v158, v154
	v_mov_b32 v159, v154
	v_mov_b32 v160, v154
	v_mov_b32 v161, v154
	global_load_lds_dwordx4 v[2:3], off
	s_cselect_b32 s9, s67, s69
	s_cselect_b32 s8, s27, s68
	s_add_i32 m0, s22, 0x400
	s_cmp_lt_i32 s26, 2
	s_cselect_b64 s[26:27], -1, 0
	s_add_i32 s67, s46, 0x800
	s_ashr_i32 s68, s67, 31
	s_add_u32 s69, s49, 0x800
	s_addc_u32 s64, s64, 0
	s_add_i32 s49, s46, 0xffffe800
	s_add_u32 s70, s62, s49
	s_addc_u32 s71, s63, 0
	v_lshl_add_u64 v[2:3], s[8:9], 0, v[164:165]
	s_and_b64 s[8:9], s[26:27], exec
	global_load_lds_dwordx4 v[2:3], off
	s_cselect_b32 s9, s64, s71
	s_cselect_b32 s8, s69, s70
	s_add_i32 m0, s22, 0x800
	s_add_u32 s62, s62, 0x4000
	s_addc_u32 s63, s63, 0
	s_add_u32 s53, s53, 0x2000
	s_addc_u32 s55, s55, 0
	s_add_u32 s64, s53, s46
	s_addc_u32 s69, s55, s47
	s_add_u32 s70, s62, s52
	s_addc_u32 s71, s63, 0
	v_lshl_add_u64 v[2:3], s[8:9], 0, v[164:165]
	s_and_b64 s[8:9], s[10:11], exec
	global_load_lds_dwordx4 v[2:3], off
	s_cselect_b32 s9, s69, s71
	s_cselect_b32 s8, s64, s70
	s_add_i32 m0, s22, 0x6000
	s_add_u32 s64, s53, s65
	s_addc_u32 s65, s55, s66
	s_add_u32 s66, s62, s48
	s_addc_u32 s69, s63, 0
	v_lshl_add_u64 v[2:3], s[8:9], 0, v[164:165]
	s_and_b64 s[8:9], s[10:11], exec
	global_load_lds_dwordx4 v[2:3], off
	s_cselect_b32 s9, s65, s69
	s_cselect_b32 s8, s64, s66
	s_add_i32 m0, s22, 0x6400
	s_add_u32 s53, s53, s67
	s_addc_u32 s55, s55, s68
	s_add_u32 s62, s62, s49
	s_addc_u32 s63, s63, 0
	v_lshl_add_u64 v[2:3], s[8:9], 0, v[164:165]
	s_and_b64 s[8:9], s[26:27], exec
	s_cselect_b32 s9, s55, s63
	s_cselect_b32 s8, s53, s62
	global_load_lds_dwordx4 v[2:3], off
	v_lshl_add_u64 v[2:3], s[8:9], 0, v[164:165]
	s_add_i32 m0, s22, 0x6800
	s_waitcnt vmcnt(0)
	v_mul_f32_e32 v19, 0x4f800000, v18
	global_load_lds_dwordx4 v[2:3], off
	s_waitcnt vmcnt(3)
	s_barrier
	ds_read_b128 v[2:5], v171
	ds_read_b128 v[6:9], v171 offset:1024
	v_cmp_gt_f32_e32 vcc, s39, v18
	s_waitcnt lgkmcnt(0)
	v_mfma_scale_f32_32x32x64_f8f6f4 v[2:17], v[2:9], v[146:153], 0, v174, v174 op_sel_hi:[0,0,0]
	v_cndmask_b32_e32 v43, v18, v19, vcc
	v_sqrt_f32_e32 v26, v43
	ds_read_b128 v[18:21], v171 offset:2048
	ds_read_b128 v[22:25], v171 offset:3072
	s_add_u32 s44, s44, s46
	s_addc_u32 s45, s45, s47
	v_add_u32_e32 v27, -1, v26
	v_fma_f32 v28, -v27, v26, v43
	v_cmp_ge_f32_e64 s[8:9], 0, v28
	v_add_u32_e32 v28, 1, v26
	s_add_u32 s46, s50, s49
	v_cndmask_b32_e64 v27, v26, v27, s[8:9]
	v_fma_f32 v26, -v28, v26, v43
	v_cmp_lt_f32_e64 s[8:9], 0, v26
	s_addc_u32 s47, s51, 0
	s_add_u32 s48, s50, s48
	v_cndmask_b32_e64 v34, v27, v28, s[8:9]
	s_waitcnt lgkmcnt(0)
	v_mfma_scale_f32_32x32x64_f8f6f4 v[18:33], v[18:25], v[146:153], 0, v174, v174 op_sel_hi:[0,0,0]
	v_max3_f32 v2, v2, s40, v3
	v_max3_f32 v2, v2, v4, v5
	v_max3_f32 v2, v2, v6, v7
	v_max3_f32 v2, v2, v8, v9
	v_mul_f32_e32 v35, 0x37800000, v34
	v_max3_f32 v2, v2, v10, v11
	v_cndmask_b32_e32 v44, v34, v35, vcc
	ds_read_b128 v[34:37], v171 offset:4096
	ds_read_b128 v[38:41], v171 offset:5120
	v_max3_f32 v2, v2, v12, v13
	v_max3_f32 v2, v2, v14, v15
	v_max3_f32 v2, v2, v16, v17
	v_cmp_lt_i32_e32 vcc, v176, v177
	s_addc_u32 s49, s51, 0
	s_add_u32 s50, s50, s52
	s_addc_u32 s51, s51, 0
	s_nop 3
	v_max3_f32 v2, v2, v18, v19
	v_max3_f32 v2, v2, v20, v21
	v_max3_f32 v18, v2, v22, v23
	s_waitcnt lgkmcnt(0)
	v_mfma_scale_f32_32x32x64_f8f6f4 v[2:17], v[34:41], v[146:153], 0, v174, v174 op_sel_hi:[0,0,0]
	v_max3_f32 v18, v18, v24, v25
	v_max3_f32 v18, v18, v26, v27
	v_max3_f32 v18, v18, v28, v29
	v_max3_f32 v18, v18, v30, v31
	v_max3_f32 v26, v18, v32, v33
	ds_read_b128 v[18:21], v171 offset:6144
	ds_read_b128 v[22:25], v171 offset:7168
	s_mov_b32 s55, 0
	s_mov_b32 s52, 0
	v_mov_b32_e32 v27, v163
	v_mov_b32_e32 v28, v163
	v_mov_b32_e32 v29, v163
	v_mov_b32_e32 v30, v163
	v_mov_b32_e32 v31, v163
	v_mov_b32_e32 v32, v163
	v_mov_b32_e32 v33, v163
	s_nop 3
	v_max3_f32 v2, v26, v2, v3
	v_max3_f32 v2, v2, v4, v5
	v_max3_f32 v2, v2, v6, v7
	v_max3_f32 v2, v2, v8, v9
	v_max3_f32 v2, v2, v10, v11
	v_max3_f32 v2, v2, v12, v13
	v_max3_f32 v2, v2, v14, v15
	v_max3_f32 v26, v2, v16, v17
	s_waitcnt lgkmcnt(0)
	v_mfma_scale_f32_32x32x64_f8f6f4 v[2:17], v[18:25], v[146:153], 0, v174, v174 op_sel_hi:[0,0,0]
	v_mov_b32_e32 v18, 0
	v_mov_b32_e32 v19, v163
	v_mov_b32_e32 v20, v163
	v_mov_b32_e32 v21, v163
	v_mov_b32_e32 v22, v163
	v_mov_b32_e32 v23, v163
	v_mov_b32_e32 v24, v163
	v_mov_b32_e32 v25, v163
	v_mov_b32_e32 v34, 0
	v_mov_b32_e32 v35, v163
	v_mov_b32_e32 v36, v163
	v_mov_b32_e32 v37, v163
	v_mov_b32_e32 v38, v163
	v_mov_b32_e32 v39, v163
	v_mov_b32_e32 v40, v163
	s_nop 4
	v_max3_f32 v2, v26, v2, v3
	v_max3_f32 v2, v2, v4, v5
	v_max3_f32 v2, v2, v6, v7
	v_max3_f32 v2, v2, v8, v9
	v_max3_f32 v2, v2, v10, v11
	v_max3_f32 v2, v2, v12, v13
	v_max3_f32 v2, v2, v14, v15
	v_cndmask_b32_e32 v3, v175, v176, vcc
	v_max3_f32 v2, v2, v16, v17
	v_lshlrev_b32_e32 v3, 2, v3
	ds_bpermute_b32 v3, v3, v2
	v_cmp_class_f32_e32 vcc, v43, v172
	v_mov_b32_e32 v5, v163
	v_mov_b32_e32 v6, v163
	v_cndmask_b32_e32 v4, v44, v43, vcc
	s_waitcnt lgkmcnt(0)
	v_max_f32_e32 v3, v3, v3
	v_mul_f32_e32 v4, v42, v4
	v_max_f32_e32 v2, v2, v3
	v_fmamk_f32 v4, v4, 0x3f90a3d7, v173
	v_add_f32_e32 v2, 0x42800000, v2
	v_min_f32_e32 v2, v4, v2
	v_add_f32_e32 v2, 0xc2ec0000, v2
	v_xor_b32_e32 v50, 0x80000000, v2
	v_mov_b32_e32 v51, v50
	v_mov_b32_e32 v52, v50
	v_mov_b32_e32 v53, v50
	v_mov_b32_e32 v54, v50
	v_mov_b32_e32 v55, v50
	v_mov_b32_e32 v56, v50
	v_mov_b32_e32 v57, v50
	v_mov_b32_e32 v58, v50
	v_mov_b32_e32 v59, v50
	v_mov_b32_e32 v60, v50
	v_mov_b32_e32 v61, v50
	v_mov_b32_e32 v62, v50
	v_mov_b32_e32 v63, v50
	v_mov_b32_e32 v64, v50
	v_mov_b32_e32 v65, v50
	v_mov_b32_e32 v2, 0
	v_mov_b32_e32 v3, v163
	v_mov_b32_e32 v4, v163
	v_mov_b32_e32 v7, v163
	v_mov_b32_e32 v8, v163
	v_mov_b32_e32 v9, v163
	v_mov_b32_e32 v10, v163
	v_mov_b32_e32 v11, v163
	v_mov_b32_e32 v12, v163
	v_mov_b32_e32 v13, v163
	v_mov_b32_e32 v14, v163
	v_mov_b32_e32 v15, v163
	v_mov_b32_e32 v16, v163
	v_mov_b32_e32 v17, v163
	v_mov_b32_e32 v26, v163
	v_mov_b32_e32 v41, v163
	v_mov_b32_e32 v42, v163
	v_mov_b32_e32 v43, v163
	v_mov_b32_e32 v44, v163
	v_mov_b32_e32 v45, v163
	v_mov_b32_e32 v46, v163
	v_mov_b32_e32 v47, v163
	v_mov_b32_e32 v48, v163
	v_mov_b32_e32 v49, v163
	v_mov_b32_e32 v66, 0
	v_mov_b32_e32 v67, v163
	v_mov_b32_e32 v68, v163
	v_mov_b32_e32 v69, v163
	v_mov_b32_e32 v70, v163
	v_mov_b32_e32 v71, v163
	v_mov_b32_e32 v72, v163
	v_mov_b32_e32 v73, v163
	v_mov_b32_e32 v74, v163
	v_mov_b32_e32 v75, v163
	v_mov_b32_e32 v76, v163
	v_mov_b32_e32 v77, v163
	v_mov_b32_e32 v78, v163
	v_mov_b32_e32 v79, v163
	v_mov_b32_e32 v80, v163
	v_mov_b32_e32 v81, v163
	v_mov_b32_e32 v82, 0
	v_mov_b32_e32 v83, v163
	v_mov_b32_e32 v84, v163
	v_mov_b32_e32 v85, v163
	v_mov_b32_e32 v86, v163
	v_mov_b32_e32 v87, v163
	v_mov_b32_e32 v88, v163
	v_mov_b32_e32 v89, v163
	v_mov_b32_e32 v90, v163
	v_mov_b32_e32 v91, v163
	v_mov_b32_e32 v92, v163
	v_mov_b32_e32 v93, v163
	v_mov_b32_e32 v94, v163
	v_mov_b32_e32 v95, v163
	v_mov_b32_e32 v96, v163
	v_mov_b32_e32 v97, v163
	s_branch .LBB0_1300
.LBB0_1299:
	s_mulk_i32 s55, 0x6000
	v_add_u32_e32 v179, s55, v171
	ds_read_b128 v[98:101], v179
	ds_read_b128 v[102:105], v179 offset:1024
	ds_read_b128 v[130:133], v179 offset:2048
	ds_read_b128 v[134:137], v179 offset:3072
	ds_read_b128 v[180:183], v179 offset:8192
	ds_read_b128 v[184:187], v179 offset:9216
	ds_read_b128 v[188:191], v179 offset:10240
	ds_read_b128 v[192:195], v179 offset:11264
	ds_read_b128 v[196:199], v179 offset:12288
	ds_read_b128 v[200:203], v179 offset:13312
	ds_read_b128 v[220:223], v179 offset:14336
	ds_read_b128 v[224:227], v179 offset:15360
	s_waitcnt lgkmcnt(0)
	v_mfma_scale_f32_32x32x64_f8f6f4 v[114:129], v[98:105], v[146:153], v[50:65], v174, v174 op_sel_hi:[0,0,0]
	ds_read_b128 v[98:101], v179 offset:4096
	ds_read_b128 v[102:105], v179 offset:5120
	ds_read_b128 v[138:141], v179 offset:6144
	ds_read_b128 v[142:145], v179 offset:7168
	s_add_i32 s52, s52, 2
	s_add_u32 s44, s44, 0x4000
	s_addc_u32 s45, s45, 0
	s_add_u32 s46, s46, 0x8000
	s_addc_u32 s47, s47, 0
	s_add_u32 s48, s48, 0x8000
	s_addc_u32 s49, s49, 0
	s_add_u32 s50, s50, 0x8000
	s_addc_u32 s51, s51, 0
	s_andn2_b64 vcc, exec, s[8:9]
	s_mov_b32 s55, s53
	s_nop 4
	v_med3_f32 v114, v114, 0, v178
	v_med3_f32 v115, v115, 0, v178
	v_cvt_pk_u8_f32 v114, v114, 0, 0
	v_med3_f32 v116, v116, 0, v178
	v_cvt_pk_u8_f32 v114, v115, 1, v114
	v_med3_f32 v117, v117, 0, v178
	v_cvt_pk_u8_f32 v114, v116, 2, v114
	v_cvt_pk_u8_f32 v228, v117, 3, v114
	v_med3_f32 v117, v118, 0, v178
	v_med3_f32 v114, v119, 0, v178
	v_cvt_pk_u8_f32 v117, v117, 0, 0
	v_med3_f32 v116, v120, 0, v178
	v_cvt_pk_u8_f32 v114, v114, 1, v117
	v_med3_f32 v117, v122, 0, v178
	v_med3_f32 v115, v121, 0, v178
	v_cvt_pk_u8_f32 v114, v116, 2, v114
	v_med3_f32 v116, v123, 0, v178
	v_cvt_pk_u8_f32 v117, v117, 0, 0
	v_cvt_pk_u8_f32 v229, v115, 3, v114
	v_med3_f32 v115, v124, 0, v178
	v_cvt_pk_u8_f32 v116, v116, 1, v117
	v_med3_f32 v117, v126, 0, v178
	v_med3_f32 v114, v125, 0, v178
	v_cvt_pk_u8_f32 v115, v115, 2, v116
	v_med3_f32 v116, v127, 0, v178
	v_cvt_pk_u8_f32 v117, v117, 0, 0
	v_cvt_pk_u8_f32 v230, v114, 3, v115
	v_med3_f32 v115, v128, 0, v178
	v_cvt_pk_u8_f32 v116, v116, 1, v117
	v_med3_f32 v114, v129, 0, v178
	v_cvt_pk_u8_f32 v115, v115, 2, v116
	v_cvt_pk_u8_f32 v231, v114, 3, v115
	v_mfma_scale_f32_32x32x64_f8f6f4 v[114:129], v[130:137], v[146:153], v[50:65], v174, v174 op_sel_hi:[0,0,0]
	s_waitcnt lgkmcnt(0)
	v_mfma_scale_f32_32x32x64_f8f6f4 v[98:113], v[98:105], v[146:153], v[50:65], v174, v174 op_sel_hi:[0,0,0]
	s_nop 15
	s_nop 1
	v_med3_f32 v114, v114, 0, v178
	v_med3_f32 v115, v115, 0, v178
	v_cvt_pk_u8_f32 v114, v114, 0, 0
	v_med3_f32 v116, v116, 0, v178
	v_cvt_pk_u8_f32 v114, v115, 1, v114
	v_med3_f32 v117, v117, 0, v178
	v_cvt_pk_u8_f32 v114, v116, 2, v114
	v_cvt_pk_u8_f32 v232, v117, 3, v114
	v_med3_f32 v117, v118, 0, v178
	v_med3_f32 v116, v119, 0, v178
	v_cvt_pk_u8_f32 v117, v117, 0, 0
	v_med3_f32 v115, v120, 0, v178
	v_cvt_pk_u8_f32 v116, v116, 1, v117
	v_med3_f32 v117, v122, 0, v178
	v_med3_f32 v114, v121, 0, v178
	v_mfma_scale_f32_32x32x64_f8f6f4 v[130:145], v[138:145], v[146:153], v[50:65], v174, v174 op_sel_hi:[0,0,0]
	v_med3_f32 v98, v98, 0, v178
	v_med3_f32 v99, v99, 0, v178
	v_cvt_pk_u8_f32 v98, v98, 0, 0
	v_cvt_pk_u8_f32 v115, v115, 2, v116
	v_med3_f32 v116, v123, 0, v178
	v_cvt_pk_u8_f32 v117, v117, 0, 0
	v_med3_f32 v100, v100, 0, v178
	v_cvt_pk_u8_f32 v98, v99, 1, v98
	v_cvt_pk_u8_f32 v233, v114, 3, v115
	v_med3_f32 v115, v124, 0, v178
	v_cvt_pk_u8_f32 v116, v116, 1, v117
	v_med3_f32 v117, v126, 0, v178
	v_med3_f32 v101, v101, 0, v178
	v_cvt_pk_u8_f32 v98, v100, 2, v98
	v_med3_f32 v114, v125, 0, v178
	v_cvt_pk_u8_f32 v115, v115, 2, v116
	v_med3_f32 v116, v127, 0, v178
	v_cvt_pk_u8_f32 v117, v117, 0, 0
	v_cvt_pk_u8_f32 v244, v101, 3, v98
	v_med3_f32 v101, v102, 0, v178
	v_cvt_pk_u8_f32 v234, v114, 3, v115
	v_med3_f32 v115, v128, 0, v178
	v_cvt_pk_u8_f32 v116, v116, 1, v117
	v_med3_f32 v100, v103, 0, v178
	v_cvt_pk_u8_f32 v101, v101, 0, 0
	v_med3_f32 v114, v129, 0, v178
	v_cvt_pk_u8_f32 v115, v115, 2, v116
	v_med3_f32 v99, v104, 0, v178
	v_cvt_pk_u8_f32 v100, v100, 1, v101
	v_med3_f32 v101, v106, 0, v178
	v_cvt_pk_u8_f32 v235, v114, 3, v115
	v_med3_f32 v98, v105, 0, v178
	v_cvt_pk_u8_f32 v99, v99, 2, v100
	v_med3_f32 v100, v107, 0, v178
	v_cvt_pk_u8_f32 v101, v101, 0, 0
	v_mfma_scale_f32_32x32x64_f8f6f4 v[66:81], v[180:187], v[228:235], v[66:81], v174, v174 op_sel_hi:[0,0,0] blgp:1
	v_cvt_pk_u8_f32 v245, v98, 3, v99
	v_med3_f32 v99, v108, 0, v178
	v_cvt_pk_u8_f32 v100, v100, 1, v101
	v_med3_f32 v101, v110, 0, v178
	v_med3_f32 v98, v109, 0, v178
	v_cvt_pk_u8_f32 v99, v99, 2, v100
	v_med3_f32 v100, v111, 0, v178
	v_cvt_pk_u8_f32 v101, v101, 0, 0
	v_cvt_pk_u8_f32 v246, v98, 3, v99
	v_med3_f32 v99, v112, 0, v178
	v_cvt_pk_u8_f32 v100, v100, 1, v101
	v_med3_f32 v101, v130, 0, v178
	v_med3_f32 v98, v113, 0, v178
	v_cvt_pk_u8_f32 v99, v99, 2, v100
	v_med3_f32 v100, v131, 0, v178
	v_mfma_scale_f32_32x32x64_f8f6f4 v[34:49], v[188:195], v[228:235], v[34:49], v174, v174 op_sel_hi:[0,0,0] blgp:1
	v_cvt_pk_u8_f32 v101, v101, 0, 0
	v_cvt_pk_u8_f32 v247, v98, 3, v99
	v_med3_f32 v99, v132, 0, v178
	v_cvt_pk_u8_f32 v100, v100, 1, v101
	v_med3_f32 v101, v134, 0, v178
	v_med3_f32 v98, v133, 0, v178
	v_cvt_pk_u8_f32 v99, v99, 2, v100
	v_med3_f32 v100, v135, 0, v178
	v_cvt_pk_u8_f32 v101, v101, 0, 0
	v_cvt_pk_u8_f32 v248, v98, 3, v99
	v_med3_f32 v99, v136, 0, v178
	v_cvt_pk_u8_f32 v100, v100, 1, v101
	v_med3_f32 v98, v137, 0, v178
	v_cvt_pk_u8_f32 v99, v99, 2, v100
	v_cvt_pk_u8_f32 v249, v98, 3, v99
	v_mfma_scale_f32_32x32x64_f8f6f4 v[18:33], v[196:203], v[228:235], v[18:33], v174, v174 op_sel_hi:[0,0,0] blgp:1
	v_med3_f32 v133, v138, 0, v178
	v_med3_f32 v132, v139, 0, v178
	v_cvt_pk_u8_f32 v133, v133, 0, 0
	v_med3_f32 v131, v140, 0, v178
	v_cvt_pk_u8_f32 v132, v132, 1, v133
	v_med3_f32 v133, v142, 0, v178
	v_med3_f32 v130, v141, 0, v178
	v_cvt_pk_u8_f32 v131, v131, 2, v132
	v_med3_f32 v132, v143, 0, v178
	v_cvt_pk_u8_f32 v133, v133, 0, 0
	v_cvt_pk_u8_f32 v250, v130, 3, v131
	v_med3_f32 v131, v144, 0, v178
	v_cvt_pk_u8_f32 v132, v132, 1, v133
	v_med3_f32 v130, v145, 0, v178
	v_cvt_pk_u8_f32 v131, v131, 2, v132
	v_mfma_scale_f32_32x32x64_f8f6f4 v[2:17], v[220:227], v[228:235], v[2:17], v174, v174 op_sel_hi:[0,0,0] blgp:1
	ds_read_b128 v[180:183], v179 offset:16384
	ds_read_b128 v[184:187], v179 offset:17408
	ds_read_b128 v[114:117], v179 offset:24576
	ds_read_b128 v[118:121], v179 offset:25600
	ds_read_b128 v[188:191], v179 offset:18432
	ds_read_b128 v[192:195], v179 offset:19456
	ds_read_b128 v[196:199], v179 offset:20480
	ds_read_b128 v[200:203], v179 offset:21504
	ds_read_b128 v[220:223], v179 offset:22528
	ds_read_b128 v[224:227], v179 offset:23552
	ds_read_b128 v[236:239], v179 offset:26624
	ds_read_b128 v[240:243], v179 offset:27648
	v_cvt_pk_u8_f32 v251, v130, 3, v131
	s_waitcnt lgkmcnt(0)
	v_mfma_scale_f32_32x32x64_f8f6f4 v[114:129], v[114:121], v[146:153], v[50:65], v174, v174 op_sel_hi:[0,0,0]
	v_mfma_scale_f32_32x32x64_f8f6f4 v[98:113], v[236:243], v[146:153], v[50:65], v174, v174 op_sel_hi:[0,0,0]
	s_nop 15
	s_nop 2
	v_med3_f32 v114, v114, 0, v178
	v_med3_f32 v115, v115, 0, v178
	v_cvt_pk_u8_f32 v114, v114, 0, 0
	v_med3_f32 v116, v116, 0, v178
	v_cvt_pk_u8_f32 v114, v115, 1, v114
	v_med3_f32 v117, v117, 0, v178
	v_cvt_pk_u8_f32 v114, v116, 2, v114
	v_cvt_pk_u8_f32 v236, v117, 3, v114
	v_med3_f32 v117, v118, 0, v178
	v_med3_f32 v116, v119, 0, v178
	v_cvt_pk_u8_f32 v117, v117, 0, 0
	v_med3_f32 v115, v120, 0, v178
	v_cvt_pk_u8_f32 v116, v116, 1, v117
	v_med3_f32 v117, v122, 0, v178
	v_med3_f32 v114, v121, 0, v178
	v_mfma_scale_f32_16x16x128_f8f6f4 v[82:85], v[154:161], v[228:235], v[82:85], v174, v174 op_sel_hi:[0,0,0] blgp:1
	v_cvt_pk_u8_f32 v115, v115, 2, v116
	v_med3_f32 v116, v123, 0, v178
	v_cvt_pk_u8_f32 v117, v117, 0, 0
	v_med3_f32 v98, v98, 0, v178
	v_cvt_pk_u8_f32 v237, v114, 3, v115
	v_med3_f32 v115, v124, 0, v178
	v_cvt_pk_u8_f32 v116, v116, 1, v117
	v_med3_f32 v117, v126, 0, v178
	v_med3_f32 v99, v99, 0, v178
	v_cvt_pk_u8_f32 v98, v98, 0, 0
	v_med3_f32 v114, v125, 0, v178
	v_cvt_pk_u8_f32 v115, v115, 2, v116
	v_med3_f32 v116, v127, 0, v178
	v_cvt_pk_u8_f32 v117, v117, 0, 0
	v_med3_f32 v100, v100, 0, v178
	v_mfma_scale_f32_32x32x64_f8f6f4 v[66:81], v[180:187], v[244:251], v[66:81], v174, v174 op_sel_hi:[0,0,0] blgp:1
	v_cvt_pk_u8_f32 v98, v99, 1, v98
	v_cvt_pk_u8_f32 v238, v114, 3, v115
	v_med3_f32 v115, v128, 0, v178
	v_cvt_pk_u8_f32 v116, v116, 1, v117
	v_med3_f32 v101, v101, 0, v178
	v_cvt_pk_u8_f32 v98, v100, 2, v98
	v_med3_f32 v114, v129, 0, v178
	v_cvt_pk_u8_f32 v115, v115, 2, v116
	v_cvt_pk_u8_f32 v240, v101, 3, v98
	v_med3_f32 v101, v102, 0, v178
	v_cvt_pk_u8_f32 v239, v114, 3, v115
	v_med3_f32 v100, v103, 0, v178
	v_cvt_pk_u8_f32 v101, v101, 0, 0
	v_med3_f32 v99, v104, 0, v178
	v_cvt_pk_u8_f32 v100, v100, 1, v101
	v_mfma_scale_f32_32x32x64_f8f6f4 v[34:49], v[188:195], v[244:251], v[34:49], v174, v174 op_sel_hi:[0,0,0] blgp:1
	v_med3_f32 v101, v106, 0, v178
	v_med3_f32 v98, v105, 0, v178
	v_cvt_pk_u8_f32 v99, v99, 2, v100
	v_med3_f32 v100, v107, 0, v178
	v_cvt_pk_u8_f32 v101, v101, 0, 0
	v_cvt_pk_u8_f32 v241, v98, 3, v99
	v_med3_f32 v99, v108, 0, v178
	v_cvt_pk_u8_f32 v100, v100, 1, v101
	v_med3_f32 v101, v110, 0, v178
	v_med3_f32 v98, v109, 0, v178
	v_cvt_pk_u8_f32 v99, v99, 2, v100
	v_med3_f32 v100, v111, 0, v178
	v_cvt_pk_u8_f32 v101, v101, 0, 0
	v_cvt_pk_u8_f32 v242, v98, 3, v99
	v_med3_f32 v99, v112, 0, v178
	v_mfma_scale_f32_32x32x64_f8f6f4 v[18:33], v[196:203], v[244:251], v[18:33], v174, v174 op_sel_hi:[0,0,0] blgp:1
	v_cvt_pk_u8_f32 v100, v100, 1, v101
	v_med3_f32 v98, v113, 0, v178
	v_cvt_pk_u8_f32 v99, v99, 2, v100
	v_cvt_pk_u8_f32 v243, v98, 3, v99
	v_mfma_scale_f32_32x32x64_f8f6f4 v[2:17], v[220:227], v[244:251], v[2:17], v174, v174 op_sel_hi:[0,0,0] blgp:1
	ds_read_b128 v[130:133], v179 offset:28672
	ds_read_b128 v[134:137], v179 offset:29696
	ds_read_b128 v[180:183], v179 offset:30720
	ds_read_b128 v[184:187], v179 offset:31744
	ds_read_b128 v[188:191], v179 offset:32768
	ds_read_b128 v[192:195], v179 offset:33792
	ds_read_b128 v[196:199], v179 offset:34816
	ds_read_b128 v[200:203], v179 offset:35840
	ds_read_b128 v[220:223], v179 offset:36864
	ds_read_b128 v[224:227], v179 offset:37888
	ds_read_b128 v[228:231], v179 offset:38912
	ds_read_b128 v[232:235], v179 offset:39936
	s_waitcnt lgkmcnt(0)
	v_mfma_scale_f32_32x32x64_f8f6f4 v[130:145], v[130:137], v[146:153], v[50:65], v174, v174 op_sel_hi:[0,0,0]
	v_mfma_scale_f32_32x32x64_f8f6f4 v[114:129], v[180:187], v[146:153], v[50:65], v174, v174 op_sel_hi:[0,0,0]
	s_nop 15
	s_nop 2
	v_med3_f32 v109, v130, 0, v178
	v_med3_f32 v108, v131, 0, v178
	v_cvt_pk_u8_f32 v109, v109, 0, 0
	v_med3_f32 v110, v134, 0, v178
	v_med3_f32 v107, v132, 0, v178
	v_cvt_pk_u8_f32 v108, v108, 1, v109
	v_med3_f32 v109, v135, 0, v178
	v_cvt_pk_u8_f32 v110, v110, 0, 0
	v_med3_f32 v111, v138, 0, v178
	v_med3_f32 v106, v133, 0, v178
	v_cvt_pk_u8_f32 v107, v107, 2, v108
	v_med3_f32 v108, v136, 0, v178
	v_cvt_pk_u8_f32 v109, v109, 1, v110
	v_med3_f32 v110, v139, 0, v178
	v_cvt_pk_u8_f32 v111, v111, 0, 0
	v_mfma_scale_f32_16x16x128_f8f6f4 v[82:85], v[154:161], v[244:251], v[82:85], v174, v174 op_sel_hi:[0,0,0] blgp:1
	v_med3_f32 v112, v142, 0, v178
	v_cvt_pk_u8_f32 v106, v106, 3, v107
	v_med3_f32 v107, v137, 0, v178
	v_cvt_pk_u8_f32 v108, v108, 2, v109
	v_med3_f32 v109, v140, 0, v178
	v_cvt_pk_u8_f32 v110, v110, 1, v111
	v_med3_f32 v111, v143, 0, v178
	v_cvt_pk_u8_f32 v112, v112, 0, 0
	v_med3_f32 v113, v114, 0, v178
	v_cvt_pk_u8_f32 v107, v107, 3, v108
	v_med3_f32 v108, v141, 0, v178
	v_cvt_pk_u8_f32 v109, v109, 2, v110
	v_med3_f32 v110, v144, 0, v178
	v_cvt_pk_u8_f32 v111, v111, 1, v112
	v_med3_f32 v112, v115, 0, v178
	v_mfma_scale_f32_32x32x64_f8f6f4 v[66:81], v[188:195], v[236:243], v[66:81], v174, v174 op_sel_hi:[0,0,0] blgp:1
	v_cvt_pk_u8_f32 v113, v113, 0, 0
	v_med3_f32 v114, v118, 0, v178
	v_cvt_pk_u8_f32 v108, v108, 3, v109
	v_med3_f32 v109, v145, 0, v178
	v_cvt_pk_u8_f32 v110, v110, 2, v111
	v_med3_f32 v111, v116, 0, v178
	v_cvt_pk_u8_f32 v112, v112, 1, v113
	v_med3_f32 v113, v119, 0, v178
	v_cvt_pk_u8_f32 v114, v114, 0, 0
	v_med3_f32 v115, v122, 0, v178
	ds_read_b128 v[98:101], v179 offset:40960
	ds_read_b128 v[102:105], v179 offset:41984
	v_cvt_pk_u8_f32 v109, v109, 3, v110
	v_med3_f32 v110, v117, 0, v178
	v_cvt_pk_u8_f32 v111, v111, 2, v112
	v_med3_f32 v112, v120, 0, v178
	v_mfma_scale_f32_32x32x64_f8f6f4 v[34:49], v[196:203], v[236:243], v[34:49], v174, v174 op_sel_hi:[0,0,0] blgp:1
	v_cvt_pk_u8_f32 v113, v113, 1, v114
	v_med3_f32 v114, v123, 0, v178
	v_cvt_pk_u8_f32 v115, v115, 0, 0
	v_med3_f32 v116, v126, 0, v178
	v_cvt_pk_u8_f32 v110, v110, 3, v111
	v_med3_f32 v111, v121, 0, v178
	v_cvt_pk_u8_f32 v112, v112, 2, v113
	v_med3_f32 v113, v124, 0, v178
	v_cvt_pk_u8_f32 v114, v114, 1, v115
	v_med3_f32 v115, v127, 0, v178
	v_cvt_pk_u8_f32 v116, v116, 0, 0
	v_cvt_pk_u8_f32 v111, v111, 3, v112
	v_med3_f32 v112, v125, 0, v178
	v_cvt_pk_u8_f32 v113, v113, 2, v114
	v_med3_f32 v114, v128, 0, v178
	v_mfma_scale_f32_32x32x64_f8f6f4 v[18:33], v[220:227], v[236:243], v[18:33], v174, v174 op_sel_hi:[0,0,0] blgp:1
	v_cvt_pk_u8_f32 v115, v115, 1, v116
	v_cvt_pk_u8_f32 v112, v112, 3, v113
	v_med3_f32 v113, v129, 0, v178
	v_cvt_pk_u8_f32 v114, v114, 2, v115
	v_cvt_pk_u8_f32 v113, v113, 3, v114
	v_mfma_scale_f32_32x32x64_f8f6f4 v[2:17], v[228:235], v[236:243], v[2:17], v174, v174 op_sel_hi:[0,0,0] blgp:1
	v_mfma_scale_f32_16x16x128_f8f6f4 v[82:85], v[154:161], v[236:243], v[82:85], v174, v174 op_sel_hi:[0,0,0] blgp:1
	s_waitcnt lgkmcnt(0)
	v_mfma_scale_f32_32x32x64_f8f6f4 v[66:81], v[98:105], v[106:113], v[66:81], v174, v174 op_sel_hi:[0,0,0] blgp:1
	ds_read_b128 v[98:101], v179 offset:43008
	ds_read_b128 v[102:105], v179 offset:44032
	s_waitcnt lgkmcnt(0)
	v_mfma_scale_f32_32x32x64_f8f6f4 v[34:49], v[98:105], v[106:113], v[34:49], v174, v174 op_sel_hi:[0,0,0] blgp:1
	ds_read_b128 v[98:101], v179 offset:45056
	ds_read_b128 v[102:105], v179 offset:46080
	s_waitcnt lgkmcnt(0)
	v_mfma_scale_f32_32x32x64_f8f6f4 v[18:33], v[98:105], v[106:113], v[18:33], v174, v174 op_sel_hi:[0,0,0] blgp:1
	ds_read_b128 v[98:101], v179 offset:47104
	ds_read_b128 v[102:105], v179 offset:48128
	s_waitcnt lgkmcnt(0)
	v_mfma_scale_f32_32x32x64_f8f6f4 v[2:17], v[98:105], v[106:113], v[2:17], v174, v174 op_sel_hi:[0,0,0] blgp:1
	v_mfma_scale_f32_16x16x128_f8f6f4 v[82:85], v[154:161], v[106:113], v[82:85], v174, v174 op_sel_hi:[0,0,0] blgp:1
	s_cbranch_vccz .LBB0_1297

.LBB0_4060:
	s_lshl_b32 s4, s44, 5
	s_lshr_b32 s2, s44, 1
	s_and_b32 s4, s4, 32
	s_ashr_i32 s0, s12, 6
	s_and_b32 s1, s12, 63
	s_add_i32 s2, s2, s34
	s_add_i32 s4, s4, s31
	s_and_b64 s[12:13], s[18:19], exec
	s_cselect_b32 s0, s2, s0
	s_cselect_b32 s1, s4, s1
	s_lshr_b32 s2, s0, 3
	s_mulk_i32 s2, 0x4100
	s_lshl_b32 s1, s1, 8
	s_and_b32 s4, s0, 7
	s_add_i32 s2, s2, s1
	v_add_u32_e32 v166, s2, v170
	s_lshl_b32 s24, s4, 7
	s_lshl_b32 s12, s4, 2
	s_mul_i32 s46, s0, 0x208000
	v_ashrrev_i32_e32 v167, 31, v166
	s_mul_hi_i32 s47, s0, 0x208000
	s_add_u32 s1, s35, s46
	v_lshlrev_b64 v[4:5], 5, v[166:167]
	s_addc_u32 s2, s36, s47
	s_mul_i32 s55, s0, 0x104000
	v_lshl_add_u64 v[4:5], s[16:17], 0, v[4:5]
	s_mov_b32 s13, s25
	s_mul_hi_i32 s64, s0, 0x104000
	s_add_u32 s4, s37, s55
	v_lshl_add_u64 v[4:5], v[4:5], 0, s[12:13]
	s_addc_u32 s5, s38, s64
	s_add_i32 s12, s0, 32
	v_lshlrev_b64 v[2:3], 10, v[166:167]
	s_ashr_i32 s13, s12, 31
	v_lshl_add_u64 v[2:3], s[22:23], 0, v[2:3]
	s_lshl_b64 s[12:13], s[12:13], 2
	v_lshl_add_u64 v[2:3], v[2:3], 0, s[24:25]
	s_add_u32 s12, s3, s12
	s_addc_u32 s13, s30, s13
	v_lshl_add_u64 v[2:3], v[2:3], 0, v[178:179]
	global_load_dword v58, v[4:5], off
	global_load_dword v50, v163, s[12:13]
	global_load_dwordx4 v[142:145], v[2:3], off offset:16
	global_load_dwordx4 v[138:141], v[2:3], off
	global_load_dwordx4 v[150:153], v[2:3], off offset:80
	global_load_dwordx4 v[146:149], v[2:3], off offset:64
	v_readfirstlane_b32 s0, v1
	s_ashr_i32 s0, s0, 6
	s_cmp_lt_i32 s0, 6
	s_mul_i32 s48, s0, 0xc00
	s_cselect_b64 s[14:15], -1, 0
	s_add_i32 s65, s48, 0xffffc000
	s_add_u32 s6, s4, s65
	s_addc_u32 s7, s5, 0
	s_ashr_i32 s49, s48, 31
	s_add_u32 s8, s1, s48
	s_addc_u32 s9, s2, s49
	s_and_b64 s[12:13], s[14:15], exec
	s_cselect_b32 s13, s9, s7
	s_cselect_b32 s12, s8, s6
	s_add_i32 s45, s48, 0
	s_cmp_lt_i32 s0, 5
	s_cselect_b64 s[28:29], -1, 0
	s_add_i32 s0, s48, 0x400
	s_ashr_i32 s6, s0, 31
	s_add_u32 s7, s8, 0x400
	s_addc_u32 s10, s9, 0
	s_add_i32 s52, s48, 0xffffc400
	s_add_u32 s11, s4, s52
	s_addc_u32 s33, s5, 0
	v_lshl_add_u64 v[2:3], s[12:13], 0, v[164:165]
	s_and_b64 s[12:13], s[28:29], exec
	s_mov_b32 m0, s45
	s_cselect_b32 s13, s10, s33
	s_cselect_b32 s12, s7, s11
	s_add_i32 s7, s48, 0x800
	v_lshrrev_b32 v154, 2, v0
	v_xor_b32 v154, v154, v0
	v_bfe_u32 v154, v154, 2, 1
	v_add_u32 v154, -1, v154
	v_and_b32 v154, 0x38383838, v154
	v_mov_b32 v155, v154
	v_mov_b32 v156, v154
	v_mov_b32 v157, v154
	v_mov_b32 v158, v154
	v_mov_b32 v159, v154
	v_mov_b32 v160, v154
	v_mov_b32 v161, v154
	global_load_lds_dwordx4 v[2:3], off
	s_add_i32 m0, s45, 0x400
	s_ashr_i32 s10, s7, 31
	s_add_u32 s8, s8, 0x800
	s_addc_u32 s9, s9, 0
	s_add_i32 s53, s48, 0xffffc800
	s_add_u32 s11, s4, s53
	s_addc_u32 s33, s5, 0
	v_lshl_add_u64 v[2:3], s[12:13], 0, v[164:165]
	s_and_b64 s[12:13], s[28:29], exec
	global_load_lds_dwordx4 v[2:3], off
	s_cselect_b32 s13, s9, s33
	s_cselect_b32 s12, s8, s11
	s_add_i32 m0, s45, 0x800
	s_add_u32 s4, s4, 0x2000
	s_addc_u32 s5, s5, 0
	s_add_u32 s1, s1, 0x4000
	s_addc_u32 s2, s2, 0
	s_add_u32 s8, s1, s48
	s_addc_u32 s9, s2, s49
	s_add_u32 s11, s4, s65
	s_addc_u32 s33, s5, 0
	v_lshl_add_u64 v[2:3], s[12:13], 0, v[164:165]
	s_and_b64 s[12:13], s[14:15], exec
	global_load_lds_dwordx4 v[2:3], off
	s_cselect_b32 s13, s9, s33
	s_cselect_b32 s12, s8, s11
	s_add_i32 m0, s45, 0x6000
	s_add_u32 s0, s1, s0
	s_addc_u32 s6, s2, s6
	s_add_u32 s8, s4, s52
	s_addc_u32 s9, s5, 0
	v_lshl_add_u64 v[2:3], s[12:13], 0, v[164:165]
	s_and_b64 s[12:13], s[28:29], exec
	global_load_lds_dwordx4 v[2:3], off
	s_cselect_b32 s13, s6, s9
	s_cselect_b32 s12, s0, s8
	s_add_i32 m0, s45, 0x6400
	s_add_u32 s0, s1, s7
	s_addc_u32 s1, s2, s10
	s_add_u32 s2, s4, s53
	s_addc_u32 s4, s5, 0
	v_lshl_add_u64 v[2:3], s[12:13], 0, v[164:165]
	s_and_b64 s[12:13], s[28:29], exec
	s_cselect_b32 s13, s1, s4
	s_cselect_b32 s12, s0, s2
	global_load_lds_dwordx4 v[2:3], off
	v_lshl_add_u64 v[2:3], s[12:13], 0, v[164:165]
	s_add_i32 m0, s45, 0x6800
	s_waitcnt vmcnt(0)
	v_mul_f32_e32 v51, 0x4f800000, v50
	global_load_lds_dwordx4 v[2:3], off
	s_waitcnt vmcnt(3)
	s_barrier
	ds_read_b128 v[2:5], v171
	ds_read_b128 v[6:9], v171 offset:1024
	s_waitcnt lgkmcnt(0)
	v_mfma_scale_f32_32x32x64_f8f6f4 v[2:17], v[2:9], v[138:145], 0, v174, v174 op_sel_hi:[0,0,0]
	ds_read_b128 v[18:21], v171 offset:2048
	ds_read_b128 v[22:25], v171 offset:3072
	v_cmp_gt_f32_e32 vcc, s39, v50
	s_add_u32 s46, s46, s48
	s_addc_u32 s47, s47, s49
	v_cndmask_b32_e32 v59, v50, v51, vcc
	v_sqrt_f32_e32 v60, v59
	s_add_u32 s48, s55, s53
	s_addc_u32 s49, s64, 0
	s_add_u32 s52, s55, s52
	v_add_u32_e32 v61, -1, v60
	v_fma_f32 v62, -v61, v60, v59
	v_cmp_ge_f32_e64 s[12:13], 0, v62
	v_add_u32_e32 v62, 1, v60
	s_addc_u32 s53, s64, 0
	v_cndmask_b32_e64 v61, v60, v61, s[12:13]
	s_waitcnt lgkmcnt(0)
	v_mfma_scale_f32_32x32x64_f8f6f4 v[2:17], v[18:25], v[146:153], v[2:17], v174, v174 op_sel_hi:[0,0,0]
	ds_read_b128 v[18:21], v171 offset:4096
	ds_read_b128 v[22:25], v171 offset:5120
	ds_read_b128 v[34:37], v171 offset:6144
	ds_read_b128 v[38:41], v171 offset:7168
	v_fma_f32 v60, -v62, v60, v59
	v_cmp_lt_f32_e64 s[12:13], 0, v60
	s_add_u32 s55, s55, s65
	s_addc_u32 s64, s64, 0
	v_cndmask_b32_e64 v60, v61, v62, s[12:13]
	s_mov_b32 s67, 0
	s_mov_b32 s65, 0
	v_mov_b32_e32 v61, v163
	v_mov_b32_e32 v62, v163
	v_mov_b32_e32 v63, v163
	v_mov_b32_e32 v64, v163
	v_mov_b32_e32 v65, v163
	s_nop 3
	v_max3_f32 v2, v2, s41, v3
	s_waitcnt lgkmcnt(0)
	v_mfma_scale_f32_32x32x64_f8f6f4 v[18:33], v[18:25], v[138:145], 0, v174, v174 op_sel_hi:[0,0,0]
	v_max3_f32 v2, v2, v4, v5
	v_max3_f32 v2, v2, v6, v7
	v_max3_f32 v2, v2, v8, v9
	v_max3_f32 v2, v2, v10, v11
	v_max3_f32 v2, v2, v12, v13
	v_max3_f32 v2, v2, v14, v15
	v_max3_f32 v2, v2, v16, v17
	v_mfma_scale_f32_32x32x64_f8f6f4 v[18:33], v[34:41], v[146:153], v[18:33], v174, v174 op_sel_hi:[0,0,0]
	ds_read_b128 v[34:37], v171 offset:8192
	ds_read_b128 v[38:41], v171 offset:9216
	ds_read_b128 v[50:53], v171 offset:10240
	ds_read_b128 v[54:57], v171 offset:11264
	s_waitcnt lgkmcnt(0)
	v_mfma_scale_f32_32x32x64_f8f6f4 v[34:49], v[34:41], v[138:145], 0, v174, v174 op_sel_hi:[0,0,0]
	s_nop 13
	v_max3_f32 v2, v2, v18, v19
	v_max3_f32 v2, v2, v20, v21
	v_max3_f32 v18, v2, v22, v23
	v_max3_f32 v18, v18, v24, v25
	v_max3_f32 v18, v18, v26, v27
	v_max3_f32 v18, v18, v28, v29
	v_max3_f32 v18, v18, v30, v31
	v_max3_f32 v26, v18, v32, v33
	v_mov_b32_e32 v27, v163
	v_mov_b32_e32 v28, v163
	v_mov_b32_e32 v29, v163
	v_mov_b32_e32 v30, v163
	v_mov_b32_e32 v31, v163
	v_mov_b32_e32 v32, v163
	v_mov_b32_e32 v33, v163
	v_mfma_scale_f32_32x32x64_f8f6f4 v[34:49], v[50:57], v[146:153], v[34:49], v174, v174 op_sel_hi:[0,0,0]
	v_mul_f32_e32 v50, 0x37800000, v60
	v_cndmask_b32_e32 v60, v60, v50, vcc
	ds_read_b128 v[50:53], v171 offset:12288
	ds_read_b128 v[54:57], v171 offset:13312
	ds_read_b128 v[18:21], v171 offset:14336
	ds_read_b128 v[22:25], v171 offset:15360
	v_cmp_lt_i32_e32 vcc, v176, v177
	s_nop 12
	v_max3_f32 v26, v26, v34, v35
	s_waitcnt lgkmcnt(0)
	v_mfma_scale_f32_32x32x64_f8f6f4 v[2:17], v[50:57], v[138:145], 0, v174, v174 op_sel_hi:[0,0,0]
	v_max3_f32 v26, v26, v36, v37
	v_max3_f32 v26, v26, v38, v39
	v_max3_f32 v26, v26, v40, v41
	v_max3_f32 v26, v26, v42, v43
	v_max3_f32 v26, v26, v44, v45
	v_max3_f32 v26, v26, v46, v47
	v_max3_f32 v26, v26, v48, v49
	v_mov_b32_e32 v50, 0
	v_mov_b32_e32 v51, v163
	v_mov_b32_e32 v52, v163
	v_mov_b32_e32 v53, v163
	v_mov_b32_e32 v54, v163
	v_mov_b32_e32 v55, v163
	v_mov_b32_e32 v56, v163
	v_mov_b32_e32 v57, v163
	v_mfma_scale_f32_32x32x64_f8f6f4 v[2:17], v[18:25], v[146:153], v[2:17], v174, v174 op_sel_hi:[0,0,0]
	v_mov_b32_e32 v18, 0
	v_mov_b32_e32 v19, v163
	v_mov_b32_e32 v20, v163
	v_mov_b32_e32 v21, v163
	v_mov_b32_e32 v22, v163
	v_mov_b32_e32 v23, v163
	v_mov_b32_e32 v24, v163
	v_mov_b32_e32 v25, v163
	s_nop 11
	v_max3_f32 v2, v26, v2, v3
	v_max3_f32 v2, v2, v4, v5
	v_max3_f32 v2, v2, v6, v7
	v_max3_f32 v2, v2, v8, v9
	v_max3_f32 v2, v2, v10, v11
	v_max3_f32 v2, v2, v12, v13
	v_max3_f32 v2, v2, v14, v15
	v_cndmask_b32_e32 v3, v175, v176, vcc
	v_max3_f32 v2, v2, v16, v17
	v_lshlrev_b32_e32 v3, 2, v3
	ds_bpermute_b32 v3, v3, v2
	v_cmp_class_f32_e32 vcc, v59, v172
	v_mov_b32_e32 v26, v163
	v_mov_b32_e32 v5, v163
	v_cndmask_b32_e32 v4, v60, v59, vcc
	s_waitcnt lgkmcnt(0)
	v_max_f32_e32 v3, v3, v3
	v_mul_f32_e32 v4, v58, v4
	v_max_f32_e32 v2, v2, v3
	v_fmamk_f32 v4, v4, 0x3f90a3d7, v173
	v_add_f32_e32 v2, 0x42800000, v2
	v_min_f32_e32 v2, v4, v2
	v_add_f32_e32 v2, 0xc2ec0000, v2
	v_xor_b32_e32 v34, 0x80000000, v2
	v_mov_b32_e32 v35, v34
	v_mov_b32_e32 v36, v34
	v_mov_b32_e32 v37, v34
	v_mov_b32_e32 v38, v34
	v_mov_b32_e32 v39, v34
	v_mov_b32_e32 v40, v34
	v_mov_b32_e32 v41, v34
	v_mov_b32_e32 v42, v34
	v_mov_b32_e32 v43, v34
	v_mov_b32_e32 v44, v34
	v_mov_b32_e32 v45, v34
	v_mov_b32_e32 v46, v34
	v_mov_b32_e32 v47, v34
	v_mov_b32_e32 v48, v34
	v_mov_b32_e32 v49, v34
	v_mov_b32_e32 v58, v163
	v_mov_b32_e32 v59, v163
	v_mov_b32_e32 v60, v163
	v_mov_b32_e32 v2, 0
	v_mov_b32_e32 v3, v163
	v_mov_b32_e32 v4, v163
	v_mov_b32_e32 v6, v163
	v_mov_b32_e32 v7, v163
	v_mov_b32_e32 v8, v163
	v_mov_b32_e32 v9, v163
	v_mov_b32_e32 v10, v163
	v_mov_b32_e32 v11, v163
	v_mov_b32_e32 v12, v163
	v_mov_b32_e32 v13, v163
	v_mov_b32_e32 v14, v163
	v_mov_b32_e32 v15, v163
	v_mov_b32_e32 v16, v163
	v_mov_b32_e32 v17, v163
	s_branch .LBB0_4062
.LBB0_4061:
	s_mul_i32 s0, s67, 0x6000
	v_add_u32_e32 v167, s0, v171
	ds_read_b128 v[82:85], v167
	ds_read_b128 v[86:89], v167 offset:1024
	ds_read_b128 v[66:69], v167 offset:4096
	ds_read_b128 v[70:73], v167 offset:5120
	ds_read_b128 v[90:93], v167 offset:2048
	ds_read_b128 v[94:97], v167 offset:3072
	ds_read_b128 v[98:101], v167 offset:6144
	ds_read_b128 v[102:105], v167 offset:7168
	ds_read_b128 v[190:193], v167 offset:16384
	ds_read_b128 v[194:197], v167 offset:17408
	ds_read_b128 v[198:201], v167 offset:18432
	ds_read_b128 v[202:205], v167 offset:19456
	s_waitcnt lgkmcnt(0)
	v_mfma_scale_f32_32x32x64_f8f6f4 v[66:81], v[66:73], v[138:145], v[34:49], v174, v174 op_sel_hi:[0,0,0]
	s_add_i32 s65, s65, 2
	s_add_u32 s46, s46, 0x8000
	s_addc_u32 s47, s47, 0
	s_add_u32 s48, s48, 0x4000
	s_addc_u32 s49, s49, 0
	s_add_u32 s52, s52, 0x4000
	s_addc_u32 s53, s53, 0
	s_add_u32 s55, s55, 0x4000
	s_addc_u32 s64, s64, 0
	s_andn2_b64 vcc, exec, s[12:13]
	s_mov_b32 s67, s66
	v_mfma_scale_f32_32x32x64_f8f6f4 v[122:137], v[82:89], v[138:145], v[34:49], v174, v174 op_sel_hi:[0,0,0]
	v_mfma_scale_f32_32x32x64_f8f6f4 v[66:81], v[98:105], v[146:153], v[66:81], v174, v174 op_sel_hi:[0,0,0]
	ds_read_b128 v[82:85], v167 offset:12288
	ds_read_b128 v[86:89], v167 offset:13312
	ds_read_b128 v[98:101], v167 offset:8192
	ds_read_b128 v[102:105], v167 offset:9216
	ds_read_b128 v[206:209], v167 offset:10240
	ds_read_b128 v[210:213], v167 offset:11264
	ds_read_b128 v[106:109], v167 offset:14336
	ds_read_b128 v[110:113], v167 offset:15360
	s_nop 11
	v_med3_f32 v66, v66, 0, v180
	v_mfma_scale_f32_32x32x64_f8f6f4 v[122:137], v[90:97], v[146:153], v[122:137], v174, v174 op_sel_hi:[0,0,0]
	v_med3_f32 v67, v67, 0, v180
	v_cvt_pk_u8_f32 v66, v66, 0, 0
	v_med3_f32 v68, v68, 0, v180
	v_cvt_pk_u8_f32 v66, v67, 1, v66
	v_med3_f32 v69, v69, 0, v180
	v_cvt_pk_u8_f32 v66, v68, 2, v66
	v_med3_f32 v68, v71, 0, v180
	v_med3_f32 v67, v72, 0, v180
	s_waitcnt lgkmcnt(0)
	v_mfma_scale_f32_32x32x64_f8f6f4 v[82:97], v[82:89], v[138:145], v[34:49], v174, v174 op_sel_hi:[0,0,0]
	v_mfma_scale_f32_32x32x64_f8f6f4 v[82:97], v[106:113], v[146:153], v[82:97], v174, v174 op_sel_hi:[0,0,0]
	v_mfma_scale_f32_32x32x64_f8f6f4 v[106:121], v[98:105], v[138:145], v[34:49], v174, v174 op_sel_hi:[0,0,0]
	s_nop 7
	v_med3_f32 v101, v122, 0, v180
	v_med3_f32 v100, v123, 0, v180
	v_cvt_pk_u8_f32 v101, v101, 0, 0
	v_med3_f32 v99, v124, 0, v180
	v_cvt_pk_u8_f32 v100, v100, 1, v101
	v_med3_f32 v101, v126, 0, v180
	v_cvt_pk_u8_f32 v126, v69, 3, v66
	v_med3_f32 v69, v70, 0, v180
	v_med3_f32 v98, v125, 0, v180
	v_cvt_pk_u8_f32 v99, v99, 2, v100
	v_med3_f32 v100, v127, 0, v180
	v_cvt_pk_u8_f32 v101, v101, 0, 0
	v_cvt_pk_u8_f32 v69, v69, 0, 0
	v_cvt_pk_u8_f32 v122, v98, 3, v99
	v_med3_f32 v99, v128, 0, v180
	v_cvt_pk_u8_f32 v100, v100, 1, v101
	v_med3_f32 v101, v130, 0, v180
	v_cvt_pk_u8_f32 v68, v68, 1, v69
	v_med3_f32 v69, v74, 0, v180
	v_med3_f32 v98, v129, 0, v180
	v_cvt_pk_u8_f32 v99, v99, 2, v100
	v_med3_f32 v100, v131, 0, v180
	v_cvt_pk_u8_f32 v101, v101, 0, 0
	v_med3_f32 v66, v73, 0, v180
	v_cvt_pk_u8_f32 v67, v67, 2, v68
	v_med3_f32 v68, v75, 0, v180
	v_cvt_pk_u8_f32 v69, v69, 0, 0
	v_cvt_pk_u8_f32 v123, v98, 3, v99
	v_med3_f32 v99, v132, 0, v180
	v_cvt_pk_u8_f32 v100, v100, 1, v101
	v_med3_f32 v101, v134, 0, v180
	v_cvt_pk_u8_f32 v127, v66, 3, v67
	v_med3_f32 v67, v76, 0, v180
	v_cvt_pk_u8_f32 v68, v68, 1, v69
	v_med3_f32 v69, v78, 0, v180
	v_med3_f32 v98, v133, 0, v180
	v_cvt_pk_u8_f32 v99, v99, 2, v100
	v_med3_f32 v100, v135, 0, v180
	v_cvt_pk_u8_f32 v101, v101, 0, 0
	v_med3_f32 v66, v77, 0, v180
	v_cvt_pk_u8_f32 v67, v67, 2, v68
	v_med3_f32 v68, v79, 0, v180
	v_cvt_pk_u8_f32 v69, v69, 0, 0
	v_cvt_pk_u8_f32 v124, v98, 3, v99
	v_med3_f32 v99, v136, 0, v180
	v_cvt_pk_u8_f32 v100, v100, 1, v101
	v_cvt_pk_u8_f32 v128, v66, 3, v67
	v_med3_f32 v67, v80, 0, v180
	v_cvt_pk_u8_f32 v68, v68, 1, v69
	v_mfma_scale_f32_32x32x64_f8f6f4 v[106:121], v[206:213], v[146:153], v[106:121], v174, v174 op_sel_hi:[0,0,0]
	v_med3_f32 v98, v137, 0, v180
	v_cvt_pk_u8_f32 v99, v99, 2, v100
	v_med3_f32 v66, v81, 0, v180
	v_cvt_pk_u8_f32 v67, v67, 2, v68
	v_cvt_pk_u8_f32 v125, v98, 3, v99
	v_cvt_pk_u8_f32 v129, v66, 3, v67
	v_med3_f32 v82, v82, 0, v180
	v_med3_f32 v83, v83, 0, v180
	v_cvt_pk_u8_f32 v82, v82, 0, 0
	v_med3_f32 v84, v84, 0, v180
	v_cvt_pk_u8_f32 v82, v83, 1, v82
	v_med3_f32 v85, v85, 0, v180
	v_cvt_pk_u8_f32 v82, v84, 2, v82
	v_med3_f32 v84, v87, 0, v180
	v_med3_f32 v83, v88, 0, v180
	v_mfma_scale_f32_32x32x64_f8f6f4 v[18:33], v[190:197], v[122:129], v[18:33], v174, v174 op_sel_hi:[0,0,0] blgp:1
	s_nop 3
	v_med3_f32 v106, v106, 0, v180
	v_med3_f32 v107, v107, 0, v180
	v_cvt_pk_u8_f32 v106, v106, 0, 0
	v_med3_f32 v108, v108, 0, v180
	v_cvt_pk_u8_f32 v106, v107, 1, v106
	v_med3_f32 v109, v109, 0, v180
	v_cvt_pk_u8_f32 v106, v108, 2, v106
	v_med3_f32 v108, v111, 0, v180
	v_med3_f32 v107, v112, 0, v180
	v_med3_f32 v114, v114, 0, v180
	v_med3_f32 v115, v115, 0, v180
	v_cvt_pk_u8_f32 v114, v114, 0, 0
	v_med3_f32 v116, v116, 0, v180
	v_cvt_pk_u8_f32 v114, v115, 1, v114
	v_med3_f32 v117, v117, 0, v180
	v_mfma_scale_f32_32x32x64_f8f6f4 v[2:17], v[198:205], v[122:129], v[2:17], v174, v174 op_sel_hi:[0,0,0] blgp:1
	ds_read_b128 v[190:193], v167 offset:20480
	ds_read_b128 v[194:197], v167 offset:21504
	ds_read_b128 v[198:201], v167 offset:22528
	ds_read_b128 v[202:205], v167 offset:23552
	ds_read_b128 v[66:69], v167 offset:28672
	ds_read_b128 v[70:73], v167 offset:29696
	ds_read_b128 v[98:101], v167 offset:24576
	ds_read_b128 v[102:105], v167 offset:25600
	ds_read_b128 v[206:209], v167 offset:26624
	ds_read_b128 v[210:213], v167 offset:27648
	ds_read_b128 v[130:133], v167 offset:30720
	ds_read_b128 v[134:137], v167 offset:31744
	v_cvt_pk_u8_f32 v114, v116, 2, v114
	v_med3_f32 v116, v119, 0, v180
	v_med3_f32 v115, v120, 0, v180
	s_waitcnt lgkmcnt(0)
	v_mfma_scale_f32_32x32x64_f8f6f4 v[66:81], v[66:73], v[138:145], v[34:49], v174, v174 op_sel_hi:[0,0,0]
	v_mfma_scale_f32_32x32x64_f8f6f4 v[66:81], v[130:137], v[146:153], v[66:81], v174, v174 op_sel_hi:[0,0,0]
	v_cvt_pk_u8_f32 v130, v109, 3, v106
	v_med3_f32 v109, v110, 0, v180
	v_cvt_pk_u8_f32 v109, v109, 0, 0
	v_cvt_pk_u8_f32 v108, v108, 1, v109
	v_med3_f32 v106, v113, 0, v180
	v_cvt_pk_u8_f32 v107, v107, 2, v108
	v_cvt_pk_u8_f32 v131, v106, 3, v107
	v_cvt_pk_u8_f32 v134, v85, 3, v82
	v_med3_f32 v85, v86, 0, v180
	v_cvt_pk_u8_f32 v85, v85, 0, 0
	v_cvt_pk_u8_f32 v84, v84, 1, v85
	v_med3_f32 v85, v90, 0, v180
	v_med3_f32 v82, v89, 0, v180
	v_cvt_pk_u8_f32 v83, v83, 2, v84
	v_med3_f32 v84, v91, 0, v180
	v_mfma_scale_f32_32x32x64_f8f6f4 v[98:113], v[98:105], v[138:145], v[34:49], v174, v174 op_sel_hi:[0,0,0]
	v_cvt_pk_u8_f32 v85, v85, 0, 0
	v_cvt_pk_u8_f32 v132, v117, 3, v114
	v_med3_f32 v117, v118, 0, v180
	v_cvt_pk_u8_f32 v135, v82, 3, v83
	v_med3_f32 v83, v92, 0, v180
	v_cvt_pk_u8_f32 v84, v84, 1, v85
	v_med3_f32 v85, v94, 0, v180
	v_cvt_pk_u8_f32 v117, v117, 0, 0
	v_med3_f32 v82, v93, 0, v180
	v_cvt_pk_u8_f32 v83, v83, 2, v84
	v_med3_f32 v84, v95, 0, v180
	v_cvt_pk_u8_f32 v85, v85, 0, 0
	v_cvt_pk_u8_f32 v116, v116, 1, v117
	v_cvt_pk_u8_f32 v136, v82, 3, v83
	v_med3_f32 v83, v96, 0, v180
	v_cvt_pk_u8_f32 v84, v84, 1, v85
	v_med3_f32 v114, v121, 0, v180
	v_cvt_pk_u8_f32 v115, v115, 2, v116
	v_med3_f32 v82, v97, 0, v180
	v_cvt_pk_u8_f32 v83, v83, 2, v84
	v_cvt_pk_u8_f32 v133, v114, 3, v115
	v_cvt_pk_u8_f32 v137, v82, 3, v83
	v_mfma_scale_f32_32x32x64_f8f6f4 v[98:113], v[206:213], v[146:153], v[98:113], v174, v174 op_sel_hi:[0,0,0]
	v_med3_f32 v66, v66, 0, v180
	v_med3_f32 v67, v67, 0, v180
	v_cvt_pk_u8_f32 v66, v66, 0, 0
	v_med3_f32 v68, v68, 0, v180
	v_cvt_pk_u8_f32 v66, v67, 1, v66
	v_med3_f32 v69, v69, 0, v180
	v_cvt_pk_u8_f32 v66, v68, 2, v66
	v_med3_f32 v68, v71, 0, v180
	v_med3_f32 v67, v72, 0, v180
	s_nop 10
	v_med3_f32 v98, v98, 0, v180
	v_mfma_scale_f32_16x16x128_f8f6f4 v[50:53], v[154:161], v[122:129], v[50:53], v174, v174 op_sel_hi:[0,0,0] blgp:1
	v_med3_f32 v99, v99, 0, v180
	v_cvt_pk_u8_f32 v98, v98, 0, 0
	v_med3_f32 v100, v100, 0, v180
	v_cvt_pk_u8_f32 v98, v99, 1, v98
	v_med3_f32 v101, v101, 0, v180
	v_cvt_pk_u8_f32 v98, v100, 2, v98
	v_med3_f32 v102, v102, 0, v180
	v_cvt_pk_u8_f32 v98, v101, 3, v98
	v_med3_f32 v101, v103, 0, v180
	v_cvt_pk_u8_f32 v102, v102, 0, 0
	v_med3_f32 v103, v106, 0, v180
	v_med3_f32 v100, v104, 0, v180
	v_cvt_pk_u8_f32 v101, v101, 1, v102
	v_med3_f32 v102, v107, 0, v180
	v_cvt_pk_u8_f32 v103, v103, 0, 0
	v_mfma_scale_f32_32x32x64_f8f6f4 v[18:33], v[190:197], v[130:137], v[18:33], v174, v174 op_sel_hi:[0,0,0] blgp:1
	v_med3_f32 v104, v110, 0, v180
	v_med3_f32 v99, v105, 0, v180
	v_cvt_pk_u8_f32 v100, v100, 2, v101
	v_med3_f32 v101, v108, 0, v180
	v_cvt_pk_u8_f32 v102, v102, 1, v103
	v_med3_f32 v103, v111, 0, v180
	v_cvt_pk_u8_f32 v104, v104, 0, 0
	v_cvt_pk_u8_f32 v99, v99, 3, v100
	v_med3_f32 v100, v109, 0, v180
	v_cvt_pk_u8_f32 v101, v101, 2, v102
	v_med3_f32 v102, v112, 0, v180
	v_cvt_pk_u8_f32 v103, v103, 1, v104
	v_cvt_pk_u8_f32 v100, v100, 3, v101
	v_med3_f32 v101, v113, 0, v180
	v_cvt_pk_u8_f32 v102, v102, 2, v103
	v_mfma_scale_f32_32x32x64_f8f6f4 v[2:17], v[198:205], v[130:137], v[2:17], v174, v174 op_sel_hi:[0,0,0] blgp:1
	ds_read_b128 v[114:117], v167 offset:32768
	ds_read_b128 v[118:121], v167 offset:33792
	ds_read_b128 v[82:85], v167 offset:36864
	ds_read_b128 v[86:89], v167 offset:37888
	ds_read_b128 v[190:193], v167 offset:34816
	ds_read_b128 v[194:197], v167 offset:35840
	ds_read_b128 v[122:125], v167 offset:38912
	ds_read_b128 v[126:129], v167 offset:39936
	ds_read_b128 v[198:201], v167 offset:40960
	ds_read_b128 v[202:205], v167 offset:41984
	ds_read_b128 v[206:209], v167 offset:43008
	ds_read_b128 v[210:213], v167 offset:44032
	v_cvt_pk_u8_f32 v101, v101, 3, v102
	v_cvt_pk_u8_f32 v102, v69, 3, v66
	v_med3_f32 v69, v70, 0, v180
	v_cvt_pk_u8_f32 v69, v69, 0, 0
	v_cvt_pk_u8_f32 v68, v68, 1, v69
	v_med3_f32 v69, v74, 0, v180
	v_med3_f32 v66, v73, 0, v180
	v_cvt_pk_u8_f32 v67, v67, 2, v68
	v_med3_f32 v68, v75, 0, v180
	v_cvt_pk_u8_f32 v69, v69, 0, 0
	v_cvt_pk_u8_f32 v103, v66, 3, v67
	v_med3_f32 v67, v76, 0, v180
	v_cvt_pk_u8_f32 v68, v68, 1, v69
	s_waitcnt lgkmcnt(0)
	v_mfma_scale_f32_32x32x64_f8f6f4 v[82:97], v[82:89], v[138:145], v[34:49], v174, v174 op_sel_hi:[0,0,0]
	v_med3_f32 v69, v78, 0, v180
	v_med3_f32 v66, v77, 0, v180
	v_cvt_pk_u8_f32 v67, v67, 2, v68
	v_med3_f32 v68, v79, 0, v180
	v_cvt_pk_u8_f32 v69, v69, 0, 0
	v_cvt_pk_u8_f32 v104, v66, 3, v67
	v_med3_f32 v67, v80, 0, v180
	v_cvt_pk_u8_f32 v68, v68, 1, v69
	v_med3_f32 v66, v81, 0, v180
	v_cvt_pk_u8_f32 v67, v67, 2, v68
	v_cvt_pk_u8_f32 v105, v66, 3, v67
	v_mfma_scale_f32_32x32x64_f8f6f4 v[82:97], v[122:129], v[146:153], v[82:97], v174, v174 op_sel_hi:[0,0,0]
	v_mfma_scale_f32_32x32x64_f8f6f4 v[114:129], v[114:121], v[138:145], v[34:49], v174, v174 op_sel_hi:[0,0,0]
	s_nop 15
	s_nop 2
	v_med3_f32 v81, v82, 0, v180
	v_cvt_pk_u8_f32 v81, v81, 0, 0
	v_med3_f32 v82, v86, 0, v180
	v_cvt_pk_u8_f32 v82, v82, 0, 0
	ds_read_b128 v[66:69], v167 offset:45056
	ds_read_b128 v[70:73], v167 offset:46080
	v_mfma_scale_f32_32x32x64_f8f6f4 v[114:129], v[190:197], v[146:153], v[114:129], v174, v174 op_sel_hi:[0,0,0]
	v_mfma_scale_f32_16x16x128_f8f6f4 v[50:53], v[154:161], v[130:137], v[50:53], v174, v174 op_sel_hi:[0,0,0] blgp:1
	s_nop 15
	s_nop 2
	v_med3_f32 v77, v114, 0, v180
	v_med3_f32 v76, v115, 0, v180
	v_cvt_pk_u8_f32 v77, v77, 0, 0
	v_med3_f32 v78, v118, 0, v180
	v_med3_f32 v75, v116, 0, v180
	v_cvt_pk_u8_f32 v76, v76, 1, v77
	v_med3_f32 v77, v119, 0, v180
	v_cvt_pk_u8_f32 v78, v78, 0, 0
	v_med3_f32 v79, v122, 0, v180
	v_med3_f32 v74, v117, 0, v180
	v_cvt_pk_u8_f32 v75, v75, 2, v76
	v_med3_f32 v76, v120, 0, v180
	v_cvt_pk_u8_f32 v77, v77, 1, v78
	v_med3_f32 v78, v123, 0, v180
	v_cvt_pk_u8_f32 v79, v79, 0, 0
	v_mfma_scale_f32_32x32x64_f8f6f4 v[18:33], v[198:205], v[98:105], v[18:33], v174, v174 op_sel_hi:[0,0,0] blgp:1
	v_med3_f32 v80, v126, 0, v180
	v_cvt_pk_u8_f32 v74, v74, 3, v75
	v_med3_f32 v75, v121, 0, v180
	v_cvt_pk_u8_f32 v76, v76, 2, v77
	v_med3_f32 v77, v124, 0, v180
	v_cvt_pk_u8_f32 v78, v78, 1, v79
	v_med3_f32 v79, v127, 0, v180
	v_cvt_pk_u8_f32 v80, v80, 0, 0
	v_cvt_pk_u8_f32 v75, v75, 3, v76
	v_med3_f32 v76, v125, 0, v180
	v_cvt_pk_u8_f32 v77, v77, 2, v78
	v_med3_f32 v78, v128, 0, v180
	v_cvt_pk_u8_f32 v79, v79, 1, v80
	v_med3_f32 v80, v83, 0, v180
	v_cvt_pk_u8_f32 v76, v76, 3, v77
	v_mfma_scale_f32_32x32x64_f8f6f4 v[2:17], v[206:213], v[98:105], v[2:17], v174, v174 op_sel_hi:[0,0,0] blgp:1
	v_med3_f32 v77, v129, 0, v180
	v_cvt_pk_u8_f32 v78, v78, 2, v79
	v_med3_f32 v79, v84, 0, v180
	v_cvt_pk_u8_f32 v80, v80, 1, v81
	v_med3_f32 v81, v87, 0, v180
	v_med3_f32 v83, v90, 0, v180
	v_cvt_pk_u8_f32 v77, v77, 3, v78
	v_med3_f32 v78, v85, 0, v180
	v_cvt_pk_u8_f32 v79, v79, 2, v80
	v_med3_f32 v80, v88, 0, v180
	v_cvt_pk_u8_f32 v81, v81, 1, v82
	v_med3_f32 v82, v91, 0, v180
	v_cvt_pk_u8_f32 v83, v83, 0, 0
	v_med3_f32 v84, v94, 0, v180
	v_cvt_pk_u8_f32 v78, v78, 3, v79
	v_mfma_scale_f32_16x16x128_f8f6f4 v[50:53], v[154:161], v[98:105], v[50:53], v174, v174 op_sel_hi:[0,0,0] blgp:1
	v_med3_f32 v79, v89, 0, v180
	v_cvt_pk_u8_f32 v80, v80, 2, v81
	v_med3_f32 v81, v92, 0, v180
	v_cvt_pk_u8_f32 v82, v82, 1, v83
	v_med3_f32 v83, v95, 0, v180
	v_cvt_pk_u8_f32 v84, v84, 0, 0
	v_cvt_pk_u8_f32 v79, v79, 3, v80
	v_med3_f32 v80, v93, 0, v180
	v_cvt_pk_u8_f32 v81, v81, 2, v82
	v_med3_f32 v82, v96, 0, v180
	v_cvt_pk_u8_f32 v83, v83, 1, v84
	v_cvt_pk_u8_f32 v80, v80, 3, v81
	v_med3_f32 v81, v97, 0, v180
	v_cvt_pk_u8_f32 v82, v82, 2, v83
	v_cvt_pk_u8_f32 v81, v81, 3, v82
	s_waitcnt lgkmcnt(0)
	s_nop 0
	v_mfma_scale_f32_32x32x64_f8f6f4 v[18:33], v[66:73], v[74:81], v[18:33], v174, v174 op_sel_hi:[0,0,0] blgp:1
	ds_read_b128 v[66:69], v167 offset:47104
	ds_read_b128 v[70:73], v167 offset:48128
	s_waitcnt lgkmcnt(0)
	v_mfma_scale_f32_32x32x64_f8f6f4 v[2:17], v[66:73], v[74:81], v[2:17], v174, v174 op_sel_hi:[0,0,0] blgp:1
	v_mfma_scale_f32_16x16x128_f8f6f4 v[50:53], v[154:161], v[74:81], v[50:53], v174, v174 op_sel_hi:[0,0,0] blgp:1
	s_cbranch_vccz .LBB0_4059

.LBB0_4070:
	s_lshl_b32 s4, s42, 5
	s_lshr_b32 s2, s42, 1
	s_and_b32 s4, s4, 32
	s_ashr_i32 s0, s12, 6
	s_and_b32 s1, s12, 63
	s_add_i32 s2, s2, s34
	s_add_i32 s4, s4, s31
	s_and_b64 s[12:13], s[18:19], exec
	s_cselect_b32 s0, s2, s0
	s_cselect_b32 s1, s4, s1
	s_ashr_i32 s2, s0, 3
	s_mul_i32 s4, s2, 0x4100
	s_lshl_b32 s1, s1, 8
	s_add_i32 s4, s4, s1
	v_add_u32_e32 v166, s4, v170
	v_ashrrev_i32_e32 v167, 31, v166
	s_and_b32 s43, s0, 7
	v_lshlrev_b64 v[2:3], 9, v[166:167]
	v_lshl_add_u64 v[2:3], s[20:21], 0, v[2:3]
	s_lshl_b32 s24, s43, 6
	v_lshl_add_u64 v[2:3], v[2:3], 0, s[24:25]
	s_lshl_b32 s24, s43, 2
	s_mul_i32 s44, s0, 0x104000
	s_mul_hi_i32 s45, s0, 0x104000
	s_add_u32 s1, s35, s44
	s_addc_u32 s4, s36, s45
	s_lshl_b32 s2, s2, 2
	s_bfe_u32 s5, s0, 0x20001
	s_or_b32 s52, s2, s5
	s_mul_hi_i32 s53, s52, 0x208000
	s_mul_i32 s52, s52, 0x208000
	s_add_u32 s2, s37, s52
	s_addc_u32 s5, s38, s53
	s_add_i32 s12, s0, 16
	s_ashr_i32 s13, s12, 31
	v_lshlrev_b64 v[4:5], 5, v[166:167]
	s_lshl_b64 s[12:13], s[12:13], 2
	v_lshl_add_u64 v[4:5], s[16:17], 0, v[4:5]
	s_add_u32 s12, s3, s12
	v_lshl_add_u64 v[4:5], v[4:5], 0, s[24:25]
	s_addc_u32 s13, s28, s13
	global_load_dword v42, v[4:5], off
	global_load_dword v18, v163, s[12:13]
	v_lshl_add_u64 v[2:3], v[2:3], 0, v[210:211]
	global_load_dwordx4 v[150:153], v[2:3], off offset:16
	global_load_dwordx4 v[146:149], v[2:3], off
	v_readfirstlane_b32 s0, v1
	s_ashr_i32 s0, s0, 6
	s_cmp_lt_i32 s0, 3
	s_mul_i32 s46, s0, 0xc00
	s_cselect_b64 s[14:15], -1, 0
	s_add_i32 s55, s46, 0xffffe000
	s_add_u32 s6, s2, s55
	s_addc_u32 s7, s5, 0
	s_ashr_i32 s47, s46, 31
	s_add_u32 s8, s1, s46
	s_addc_u32 s9, s4, s47
	s_and_b64 s[12:13], s[14:15], exec
	s_cselect_b32 s13, s9, s7
	s_cselect_b32 s12, s8, s6
	s_add_i32 s6, s46, 0x400
	s_add_i32 s24, s46, 0
	s_ashr_i32 s7, s6, 31
	s_add_u32 s10, s8, 0x400
	s_addc_u32 s11, s9, 0
	s_add_i32 s48, s46, 0xffffe400
	s_add_u32 s26, s2, s48
	s_addc_u32 s27, s5, 0
	v_lshl_add_u64 v[2:3], s[12:13], 0, v[164:165]
	s_mov_b32 m0, s24
	s_and_b64 s[12:13], s[14:15], exec
	v_lshrrev_b32 v154, 2, v0
	v_xor_b32 v154, v154, v0
	v_bfe_u32 v154, v154, 2, 1
	v_add_u32 v154, -1, v154
	v_and_b32 v154, 0x38383838, v154
	v_mov_b32 v155, v154
	v_mov_b32 v156, v154
	v_mov_b32 v157, v154
	v_mov_b32 v158, v154
	v_mov_b32 v159, v154
	v_mov_b32 v160, v154
	v_mov_b32 v161, v154
	global_load_lds_dwordx4 v[2:3], off
	s_cselect_b32 s13, s11, s27
	s_cselect_b32 s12, s10, s26
	s_add_i32 m0, s24, 0x400
	s_cmp_lt_i32 s0, 2
	s_cselect_b64 s[26:27], -1, 0
	s_add_i32 s0, s46, 0x800
	s_ashr_i32 s10, s0, 31
	s_add_u32 s8, s8, 0x800
	s_addc_u32 s9, s9, 0
	s_add_i32 s49, s46, 0xffffe800
	s_add_u32 s11, s2, s49
	s_addc_u32 s33, s5, 0
	v_lshl_add_u64 v[2:3], s[12:13], 0, v[164:165]
	s_and_b64 s[12:13], s[26:27], exec
	global_load_lds_dwordx4 v[2:3], off
	s_cselect_b32 s13, s9, s33
	s_cselect_b32 s12, s8, s11
	s_add_i32 m0, s24, 0x800
	s_add_u32 s2, s2, 0x4000
	s_addc_u32 s5, s5, 0
	s_add_u32 s1, s1, 0x2000
	s_addc_u32 s4, s4, 0
	s_add_u32 s8, s1, s46
	s_addc_u32 s9, s4, s47
	s_add_u32 s11, s2, s55
	s_addc_u32 s33, s5, 0
	v_lshl_add_u64 v[2:3], s[12:13], 0, v[164:165]
	s_and_b64 s[12:13], s[14:15], exec
	global_load_lds_dwordx4 v[2:3], off
	s_cselect_b32 s13, s9, s33
	s_cselect_b32 s12, s8, s11
	s_add_i32 m0, s24, 0x6000
	s_add_u32 s6, s1, s6
	s_addc_u32 s7, s4, s7
	s_add_u32 s8, s2, s48
	s_addc_u32 s9, s5, 0
	v_lshl_add_u64 v[2:3], s[12:13], 0, v[164:165]
	s_and_b64 s[12:13], s[14:15], exec
	global_load_lds_dwordx4 v[2:3], off
	s_cselect_b32 s13, s7, s9
	s_cselect_b32 s12, s6, s8
	s_add_i32 m0, s24, 0x6400
	s_add_u32 s0, s1, s0
	s_addc_u32 s1, s4, s10
	s_add_u32 s2, s2, s49
	s_addc_u32 s4, s5, 0
	v_lshl_add_u64 v[2:3], s[12:13], 0, v[164:165]
	s_and_b64 s[12:13], s[26:27], exec
	s_cselect_b32 s13, s1, s4
	s_cselect_b32 s12, s0, s2
	global_load_lds_dwordx4 v[2:3], off
	v_lshl_add_u64 v[2:3], s[12:13], 0, v[164:165]
	s_add_i32 m0, s24, 0x6800
	s_waitcnt vmcnt(0)
	v_mul_f32_e32 v19, 0x4f800000, v18
	global_load_lds_dwordx4 v[2:3], off
	s_waitcnt vmcnt(3)
	s_barrier
	ds_read_b128 v[2:5], v171
	ds_read_b128 v[6:9], v171 offset:1024
	v_cmp_gt_f32_e32 vcc, s39, v18
	s_waitcnt lgkmcnt(0)
	v_mfma_scale_f32_32x32x64_f8f6f4 v[2:17], v[2:9], v[146:153], 0, v174, v174 op_sel_hi:[0,0,0]
	v_cndmask_b32_e32 v43, v18, v19, vcc
	v_sqrt_f32_e32 v26, v43
	ds_read_b128 v[18:21], v171 offset:2048
	ds_read_b128 v[22:25], v171 offset:3072
	s_add_u32 s44, s44, s46
	s_addc_u32 s45, s45, s47
	v_add_u32_e32 v27, -1, v26
	v_fma_f32 v28, -v27, v26, v43
	v_cmp_ge_f32_e64 s[12:13], 0, v28
	v_add_u32_e32 v28, 1, v26
	s_add_u32 s46, s52, s49
	v_cndmask_b32_e64 v27, v26, v27, s[12:13]
	v_fma_f32 v26, -v28, v26, v43
	v_cmp_lt_f32_e64 s[12:13], 0, v26
	s_addc_u32 s47, s53, 0
	s_add_u32 s48, s52, s48
	v_cndmask_b32_e64 v34, v27, v28, s[12:13]
	s_waitcnt lgkmcnt(0)
	v_mfma_scale_f32_32x32x64_f8f6f4 v[18:33], v[18:25], v[146:153], 0, v174, v174 op_sel_hi:[0,0,0]
	v_max3_f32 v2, v2, s40, v3
	v_max3_f32 v2, v2, v4, v5
	v_max3_f32 v2, v2, v6, v7
	v_max3_f32 v2, v2, v8, v9
	v_mul_f32_e32 v35, 0x37800000, v34
	v_max3_f32 v2, v2, v10, v11
	v_cndmask_b32_e32 v44, v34, v35, vcc
	ds_read_b128 v[34:37], v171 offset:4096
	ds_read_b128 v[38:41], v171 offset:5120
	v_max3_f32 v2, v2, v12, v13
	v_max3_f32 v2, v2, v14, v15
	v_max3_f32 v2, v2, v16, v17
	v_cmp_lt_i32_e32 vcc, v176, v177
	s_addc_u32 s49, s53, 0
	s_add_u32 s52, s52, s55
	s_addc_u32 s53, s53, 0
	s_nop 3
	v_max3_f32 v2, v2, v18, v19
	v_max3_f32 v2, v2, v20, v21
	v_max3_f32 v18, v2, v22, v23
	s_waitcnt lgkmcnt(0)
	v_mfma_scale_f32_32x32x64_f8f6f4 v[2:17], v[34:41], v[146:153], 0, v174, v174 op_sel_hi:[0,0,0]
	v_max3_f32 v18, v18, v24, v25
	v_max3_f32 v18, v18, v26, v27
	v_max3_f32 v18, v18, v28, v29
	v_max3_f32 v18, v18, v30, v31
	v_max3_f32 v26, v18, v32, v33
	ds_read_b128 v[18:21], v171 offset:6144
	ds_read_b128 v[22:25], v171 offset:7168
	s_mov_b32 s65, 0
	s_mov_b32 s55, 0
	v_mov_b32_e32 v27, v163
	v_mov_b32_e32 v28, v163
	v_mov_b32_e32 v29, v163
	v_mov_b32_e32 v30, v163
	v_mov_b32_e32 v31, v163
	v_mov_b32_e32 v32, v163
	v_mov_b32_e32 v33, v163
	s_nop 3
	v_max3_f32 v2, v26, v2, v3
	v_max3_f32 v2, v2, v4, v5
	v_max3_f32 v2, v2, v6, v7
	v_max3_f32 v2, v2, v8, v9
	v_max3_f32 v2, v2, v10, v11
	v_max3_f32 v2, v2, v12, v13
	v_max3_f32 v2, v2, v14, v15
	v_max3_f32 v26, v2, v16, v17
	s_waitcnt lgkmcnt(0)
	v_mfma_scale_f32_32x32x64_f8f6f4 v[2:17], v[18:25], v[146:153], 0, v174, v174 op_sel_hi:[0,0,0]
	v_mov_b32_e32 v18, 0
	v_mov_b32_e32 v19, v163
	v_mov_b32_e32 v20, v163
	v_mov_b32_e32 v21, v163
	v_mov_b32_e32 v22, v163
	v_mov_b32_e32 v23, v163
	v_mov_b32_e32 v24, v163
	v_mov_b32_e32 v25, v163
	v_mov_b32_e32 v34, 0
	v_mov_b32_e32 v35, v163
	v_mov_b32_e32 v36, v163
	v_mov_b32_e32 v37, v163
	v_mov_b32_e32 v38, v163
	v_mov_b32_e32 v39, v163
	v_mov_b32_e32 v40, v163
	s_nop 4
	v_max3_f32 v2, v26, v2, v3
	v_max3_f32 v2, v2, v4, v5
	v_max3_f32 v2, v2, v6, v7
	v_max3_f32 v2, v2, v8, v9
	v_max3_f32 v2, v2, v10, v11
	v_max3_f32 v2, v2, v12, v13
	v_max3_f32 v2, v2, v14, v15
	v_cndmask_b32_e32 v3, v175, v176, vcc
	v_max3_f32 v2, v2, v16, v17
	v_lshlrev_b32_e32 v3, 2, v3
	ds_bpermute_b32 v3, v3, v2
	v_cmp_class_f32_e32 vcc, v43, v172
	v_mov_b32_e32 v5, v163
	v_mov_b32_e32 v6, v163
	v_cndmask_b32_e32 v4, v44, v43, vcc
	s_waitcnt lgkmcnt(0)
	v_max_f32_e32 v3, v3, v3
	v_mul_f32_e32 v4, v42, v4
	v_max_f32_e32 v2, v2, v3
	v_fmamk_f32 v4, v4, 0x3f90a3d7, v173
	v_add_f32_e32 v2, 0x42800000, v2
	v_min_f32_e32 v2, v4, v2
	v_add_f32_e32 v2, 0xc2ec0000, v2
	v_xor_b32_e32 v50, 0x80000000, v2
	v_mov_b32_e32 v51, v50
	v_mov_b32_e32 v52, v50
	v_mov_b32_e32 v53, v50
	v_mov_b32_e32 v54, v50
	v_mov_b32_e32 v55, v50
	v_mov_b32_e32 v56, v50
	v_mov_b32_e32 v57, v50
	v_mov_b32_e32 v58, v50
	v_mov_b32_e32 v59, v50
	v_mov_b32_e32 v60, v50
	v_mov_b32_e32 v61, v50
	v_mov_b32_e32 v62, v50
	v_mov_b32_e32 v63, v50
	v_mov_b32_e32 v64, v50
	v_mov_b32_e32 v65, v50
	v_mov_b32_e32 v2, 0
	v_mov_b32_e32 v3, v163
	v_mov_b32_e32 v4, v163
	v_mov_b32_e32 v7, v163
	v_mov_b32_e32 v8, v163
	v_mov_b32_e32 v9, v163
	v_mov_b32_e32 v10, v163
	v_mov_b32_e32 v11, v163
	v_mov_b32_e32 v12, v163
	v_mov_b32_e32 v13, v163
	v_mov_b32_e32 v14, v163
	v_mov_b32_e32 v15, v163
	v_mov_b32_e32 v16, v163
	v_mov_b32_e32 v17, v163
	v_mov_b32_e32 v26, v163
	v_mov_b32_e32 v41, v163
	v_mov_b32_e32 v42, v163
	v_mov_b32_e32 v43, v163
	v_mov_b32_e32 v44, v163
	v_mov_b32_e32 v45, v163
	v_mov_b32_e32 v46, v163
	v_mov_b32_e32 v47, v163
	v_mov_b32_e32 v48, v163
	v_mov_b32_e32 v49, v163
	v_mov_b32_e32 v66, 0
	v_mov_b32_e32 v67, v163
	v_mov_b32_e32 v68, v163
	v_mov_b32_e32 v69, v163
	v_mov_b32_e32 v70, v163
	v_mov_b32_e32 v71, v163
	v_mov_b32_e32 v72, v163
	v_mov_b32_e32 v73, v163
	v_mov_b32_e32 v74, v163
	v_mov_b32_e32 v75, v163
	v_mov_b32_e32 v76, v163
	v_mov_b32_e32 v77, v163
	v_mov_b32_e32 v78, v163
	v_mov_b32_e32 v79, v163
	v_mov_b32_e32 v80, v163
	v_mov_b32_e32 v81, v163
	v_mov_b32_e32 v82, 0
	v_mov_b32_e32 v83, v163
	v_mov_b32_e32 v84, v163
	v_mov_b32_e32 v85, v163
	v_mov_b32_e32 v86, v163
	v_mov_b32_e32 v87, v163
	v_mov_b32_e32 v88, v163
	v_mov_b32_e32 v89, v163
	v_mov_b32_e32 v90, v163
	v_mov_b32_e32 v91, v163
	v_mov_b32_e32 v92, v163
	v_mov_b32_e32 v93, v163
	v_mov_b32_e32 v94, v163
	v_mov_b32_e32 v95, v163
	v_mov_b32_e32 v96, v163
	v_mov_b32_e32 v97, v163
	s_branch .LBB0_4072
.LBB0_4071:
	s_mul_i32 s0, s65, 0x6000
	v_add_u32_e32 v179, s0, v171
	ds_read_b128 v[98:101], v179
	ds_read_b128 v[102:105], v179 offset:1024
	ds_read_b128 v[130:133], v179 offset:2048
	ds_read_b128 v[134:137], v179 offset:3072
	ds_read_b128 v[180:183], v179 offset:8192
	ds_read_b128 v[184:187], v179 offset:9216
	ds_read_b128 v[188:191], v179 offset:10240
	ds_read_b128 v[192:195], v179 offset:11264
	ds_read_b128 v[196:199], v179 offset:12288
	ds_read_b128 v[200:203], v179 offset:13312
	ds_read_b128 v[220:223], v179 offset:14336
	ds_read_b128 v[224:227], v179 offset:15360
	s_waitcnt lgkmcnt(0)
	v_mfma_scale_f32_32x32x64_f8f6f4 v[114:129], v[98:105], v[146:153], v[50:65], v174, v174 op_sel_hi:[0,0,0]
	ds_read_b128 v[98:101], v179 offset:4096
	ds_read_b128 v[102:105], v179 offset:5120
	ds_read_b128 v[138:141], v179 offset:6144
	ds_read_b128 v[142:145], v179 offset:7168
	s_add_i32 s55, s55, 2
	s_add_u32 s44, s44, 0x4000
	s_addc_u32 s45, s45, 0
	s_add_u32 s46, s46, 0x8000
	s_addc_u32 s47, s47, 0
	s_add_u32 s48, s48, 0x8000
	s_addc_u32 s49, s49, 0
	s_add_u32 s52, s52, 0x8000
	s_addc_u32 s53, s53, 0
	s_andn2_b64 vcc, exec, s[12:13]
	s_mov_b32 s65, s64
	s_nop 4
	v_med3_f32 v114, v114, 0, v178
	v_med3_f32 v115, v115, 0, v178
	v_cvt_pk_u8_f32 v114, v114, 0, 0
	v_med3_f32 v116, v116, 0, v178
	v_cvt_pk_u8_f32 v114, v115, 1, v114
	v_med3_f32 v117, v117, 0, v178
	v_cvt_pk_u8_f32 v114, v116, 2, v114
	v_cvt_pk_u8_f32 v228, v117, 3, v114
	v_med3_f32 v117, v118, 0, v178
	v_med3_f32 v114, v119, 0, v178
	v_cvt_pk_u8_f32 v117, v117, 0, 0
	v_med3_f32 v116, v120, 0, v178
	v_cvt_pk_u8_f32 v114, v114, 1, v117
	v_med3_f32 v117, v122, 0, v178
	v_med3_f32 v115, v121, 0, v178
	v_cvt_pk_u8_f32 v114, v116, 2, v114
	v_med3_f32 v116, v123, 0, v178
	v_cvt_pk_u8_f32 v117, v117, 0, 0
	v_cvt_pk_u8_f32 v229, v115, 3, v114
	v_med3_f32 v115, v124, 0, v178
	v_cvt_pk_u8_f32 v116, v116, 1, v117
	v_med3_f32 v117, v126, 0, v178
	v_med3_f32 v114, v125, 0, v178
	v_cvt_pk_u8_f32 v115, v115, 2, v116
	v_med3_f32 v116, v127, 0, v178
	v_cvt_pk_u8_f32 v117, v117, 0, 0
	v_cvt_pk_u8_f32 v230, v114, 3, v115
	v_med3_f32 v115, v128, 0, v178
	v_cvt_pk_u8_f32 v116, v116, 1, v117
	v_med3_f32 v114, v129, 0, v178
	v_cvt_pk_u8_f32 v115, v115, 2, v116
	v_cvt_pk_u8_f32 v231, v114, 3, v115
	v_mfma_scale_f32_32x32x64_f8f6f4 v[114:129], v[130:137], v[146:153], v[50:65], v174, v174 op_sel_hi:[0,0,0]
	s_waitcnt lgkmcnt(0)
	v_mfma_scale_f32_32x32x64_f8f6f4 v[98:113], v[98:105], v[146:153], v[50:65], v174, v174 op_sel_hi:[0,0,0]
	s_nop 15
	s_nop 1
	v_med3_f32 v114, v114, 0, v178
	v_med3_f32 v115, v115, 0, v178
	v_cvt_pk_u8_f32 v114, v114, 0, 0
	v_med3_f32 v116, v116, 0, v178
	v_cvt_pk_u8_f32 v114, v115, 1, v114
	v_med3_f32 v117, v117, 0, v178
	v_cvt_pk_u8_f32 v114, v116, 2, v114
	v_cvt_pk_u8_f32 v232, v117, 3, v114
	v_med3_f32 v117, v118, 0, v178
	v_med3_f32 v116, v119, 0, v178
	v_cvt_pk_u8_f32 v117, v117, 0, 0
	v_med3_f32 v115, v120, 0, v178
	v_cvt_pk_u8_f32 v116, v116, 1, v117
	v_med3_f32 v117, v122, 0, v178
	v_med3_f32 v114, v121, 0, v178
	v_mfma_scale_f32_32x32x64_f8f6f4 v[130:145], v[138:145], v[146:153], v[50:65], v174, v174 op_sel_hi:[0,0,0]
	v_med3_f32 v98, v98, 0, v178
	v_med3_f32 v99, v99, 0, v178
	v_cvt_pk_u8_f32 v98, v98, 0, 0
	v_cvt_pk_u8_f32 v115, v115, 2, v116
	v_med3_f32 v116, v123, 0, v178
	v_cvt_pk_u8_f32 v117, v117, 0, 0
	v_med3_f32 v100, v100, 0, v178
	v_cvt_pk_u8_f32 v98, v99, 1, v98
	v_cvt_pk_u8_f32 v233, v114, 3, v115
	v_med3_f32 v115, v124, 0, v178
	v_cvt_pk_u8_f32 v116, v116, 1, v117
	v_med3_f32 v117, v126, 0, v178
	v_med3_f32 v101, v101, 0, v178
	v_cvt_pk_u8_f32 v98, v100, 2, v98
	v_med3_f32 v114, v125, 0, v178
	v_cvt_pk_u8_f32 v115, v115, 2, v116
	v_med3_f32 v116, v127, 0, v178
	v_cvt_pk_u8_f32 v117, v117, 0, 0
	v_cvt_pk_u8_f32 v244, v101, 3, v98
	v_med3_f32 v101, v102, 0, v178
	v_cvt_pk_u8_f32 v234, v114, 3, v115
	v_med3_f32 v115, v128, 0, v178
	v_cvt_pk_u8_f32 v116, v116, 1, v117
	v_med3_f32 v100, v103, 0, v178
	v_cvt_pk_u8_f32 v101, v101, 0, 0
	v_med3_f32 v114, v129, 0, v178
	v_cvt_pk_u8_f32 v115, v115, 2, v116
	v_med3_f32 v99, v104, 0, v178
	v_cvt_pk_u8_f32 v100, v100, 1, v101
	v_med3_f32 v101, v106, 0, v178
	v_cvt_pk_u8_f32 v235, v114, 3, v115
	v_med3_f32 v98, v105, 0, v178
	v_cvt_pk_u8_f32 v99, v99, 2, v100
	v_med3_f32 v100, v107, 0, v178
	v_cvt_pk_u8_f32 v101, v101, 0, 0
	v_mfma_scale_f32_32x32x64_f8f6f4 v[66:81], v[180:187], v[228:235], v[66:81], v174, v174 op_sel_hi:[0,0,0] blgp:1
	v_cvt_pk_u8_f32 v245, v98, 3, v99
	v_med3_f32 v99, v108, 0, v178
	v_cvt_pk_u8_f32 v100, v100, 1, v101
	v_med3_f32 v101, v110, 0, v178
	v_med3_f32 v98, v109, 0, v178
	v_cvt_pk_u8_f32 v99, v99, 2, v100
	v_med3_f32 v100, v111, 0, v178
	v_cvt_pk_u8_f32 v101, v101, 0, 0
	v_cvt_pk_u8_f32 v246, v98, 3, v99
	v_med3_f32 v99, v112, 0, v178
	v_cvt_pk_u8_f32 v100, v100, 1, v101
	v_med3_f32 v101, v130, 0, v178
	v_med3_f32 v98, v113, 0, v178
	v_cvt_pk_u8_f32 v99, v99, 2, v100
	v_med3_f32 v100, v131, 0, v178
	v_mfma_scale_f32_32x32x64_f8f6f4 v[34:49], v[188:195], v[228:235], v[34:49], v174, v174 op_sel_hi:[0,0,0] blgp:1
	v_cvt_pk_u8_f32 v101, v101, 0, 0
	v_cvt_pk_u8_f32 v247, v98, 3, v99
	v_med3_f32 v99, v132, 0, v178
	v_cvt_pk_u8_f32 v100, v100, 1, v101
	v_med3_f32 v101, v134, 0, v178
	v_med3_f32 v98, v133, 0, v178
	v_cvt_pk_u8_f32 v99, v99, 2, v100
	v_med3_f32 v100, v135, 0, v178
	v_cvt_pk_u8_f32 v101, v101, 0, 0
	v_cvt_pk_u8_f32 v248, v98, 3, v99
	v_med3_f32 v99, v136, 0, v178
	v_cvt_pk_u8_f32 v100, v100, 1, v101
	v_med3_f32 v98, v137, 0, v178
	v_cvt_pk_u8_f32 v99, v99, 2, v100
	v_cvt_pk_u8_f32 v249, v98, 3, v99
	v_mfma_scale_f32_32x32x64_f8f6f4 v[18:33], v[196:203], v[228:235], v[18:33], v174, v174 op_sel_hi:[0,0,0] blgp:1
	v_med3_f32 v133, v138, 0, v178
	v_med3_f32 v132, v139, 0, v178
	v_cvt_pk_u8_f32 v133, v133, 0, 0
	v_med3_f32 v131, v140, 0, v178
	v_cvt_pk_u8_f32 v132, v132, 1, v133
	v_med3_f32 v133, v142, 0, v178
	v_med3_f32 v130, v141, 0, v178
	v_cvt_pk_u8_f32 v131, v131, 2, v132
	v_med3_f32 v132, v143, 0, v178
	v_cvt_pk_u8_f32 v133, v133, 0, 0
	v_cvt_pk_u8_f32 v250, v130, 3, v131
	v_med3_f32 v131, v144, 0, v178
	v_cvt_pk_u8_f32 v132, v132, 1, v133
	v_med3_f32 v130, v145, 0, v178
	v_cvt_pk_u8_f32 v131, v131, 2, v132
	v_mfma_scale_f32_32x32x64_f8f6f4 v[2:17], v[220:227], v[228:235], v[2:17], v174, v174 op_sel_hi:[0,0,0] blgp:1
	ds_read_b128 v[180:183], v179 offset:16384
	ds_read_b128 v[184:187], v179 offset:17408
	ds_read_b128 v[114:117], v179 offset:24576
	ds_read_b128 v[118:121], v179 offset:25600
	ds_read_b128 v[188:191], v179 offset:18432
	ds_read_b128 v[192:195], v179 offset:19456
	ds_read_b128 v[196:199], v179 offset:20480
	ds_read_b128 v[200:203], v179 offset:21504
	ds_read_b128 v[220:223], v179 offset:22528
	ds_read_b128 v[224:227], v179 offset:23552
	ds_read_b128 v[236:239], v179 offset:26624
	ds_read_b128 v[240:243], v179 offset:27648
	v_cvt_pk_u8_f32 v251, v130, 3, v131
	s_waitcnt lgkmcnt(0)
	v_mfma_scale_f32_32x32x64_f8f6f4 v[114:129], v[114:121], v[146:153], v[50:65], v174, v174 op_sel_hi:[0,0,0]
	v_mfma_scale_f32_32x32x64_f8f6f4 v[98:113], v[236:243], v[146:153], v[50:65], v174, v174 op_sel_hi:[0,0,0]
	s_nop 15
	s_nop 2
	v_med3_f32 v114, v114, 0, v178
	v_med3_f32 v115, v115, 0, v178
	v_cvt_pk_u8_f32 v114, v114, 0, 0
	v_med3_f32 v116, v116, 0, v178
	v_cvt_pk_u8_f32 v114, v115, 1, v114
	v_med3_f32 v117, v117, 0, v178
	v_cvt_pk_u8_f32 v114, v116, 2, v114
	v_cvt_pk_u8_f32 v236, v117, 3, v114
	v_med3_f32 v117, v118, 0, v178
	v_med3_f32 v116, v119, 0, v178
	v_cvt_pk_u8_f32 v117, v117, 0, 0
	v_med3_f32 v115, v120, 0, v178
	v_cvt_pk_u8_f32 v116, v116, 1, v117
	v_med3_f32 v117, v122, 0, v178
	v_med3_f32 v114, v121, 0, v178
	v_mfma_scale_f32_16x16x128_f8f6f4 v[82:85], v[154:161], v[228:235], v[82:85], v174, v174 op_sel_hi:[0,0,0] blgp:1
	v_cvt_pk_u8_f32 v115, v115, 2, v116
	v_med3_f32 v116, v123, 0, v178
	v_cvt_pk_u8_f32 v117, v117, 0, 0
	v_med3_f32 v98, v98, 0, v178
	v_cvt_pk_u8_f32 v237, v114, 3, v115
	v_med3_f32 v115, v124, 0, v178
	v_cvt_pk_u8_f32 v116, v116, 1, v117
	v_med3_f32 v117, v126, 0, v178
	v_med3_f32 v99, v99, 0, v178
	v_cvt_pk_u8_f32 v98, v98, 0, 0
	v_med3_f32 v114, v125, 0, v178
	v_cvt_pk_u8_f32 v115, v115, 2, v116
	v_med3_f32 v116, v127, 0, v178
	v_cvt_pk_u8_f32 v117, v117, 0, 0
	v_med3_f32 v100, v100, 0, v178
	v_mfma_scale_f32_32x32x64_f8f6f4 v[66:81], v[180:187], v[244:251], v[66:81], v174, v174 op_sel_hi:[0,0,0] blgp:1
	v_cvt_pk_u8_f32 v98, v99, 1, v98
	v_cvt_pk_u8_f32 v238, v114, 3, v115
	v_med3_f32 v115, v128, 0, v178
	v_cvt_pk_u8_f32 v116, v116, 1, v117
	v_med3_f32 v101, v101, 0, v178
	v_cvt_pk_u8_f32 v98, v100, 2, v98
	v_med3_f32 v114, v129, 0, v178
	v_cvt_pk_u8_f32 v115, v115, 2, v116
	v_cvt_pk_u8_f32 v240, v101, 3, v98
	v_med3_f32 v101, v102, 0, v178
	v_cvt_pk_u8_f32 v239, v114, 3, v115
	v_med3_f32 v100, v103, 0, v178
	v_cvt_pk_u8_f32 v101, v101, 0, 0
	v_med3_f32 v99, v104, 0, v178
	v_cvt_pk_u8_f32 v100, v100, 1, v101
	v_mfma_scale_f32_32x32x64_f8f6f4 v[34:49], v[188:195], v[244:251], v[34:49], v174, v174 op_sel_hi:[0,0,0] blgp:1
	v_med3_f32 v101, v106, 0, v178
	v_med3_f32 v98, v105, 0, v178
	v_cvt_pk_u8_f32 v99, v99, 2, v100
	v_med3_f32 v100, v107, 0, v178
	v_cvt_pk_u8_f32 v101, v101, 0, 0
	v_cvt_pk_u8_f32 v241, v98, 3, v99
	v_med3_f32 v99, v108, 0, v178
	v_cvt_pk_u8_f32 v100, v100, 1, v101
	v_med3_f32 v101, v110, 0, v178
	v_med3_f32 v98, v109, 0, v178
	v_cvt_pk_u8_f32 v99, v99, 2, v100
	v_med3_f32 v100, v111, 0, v178
	v_cvt_pk_u8_f32 v101, v101, 0, 0
	v_cvt_pk_u8_f32 v242, v98, 3, v99
	v_med3_f32 v99, v112, 0, v178
	v_mfma_scale_f32_32x32x64_f8f6f4 v[18:33], v[196:203], v[244:251], v[18:33], v174, v174 op_sel_hi:[0,0,0] blgp:1
	v_cvt_pk_u8_f32 v100, v100, 1, v101
	v_med3_f32 v98, v113, 0, v178
	v_cvt_pk_u8_f32 v99, v99, 2, v100
	v_cvt_pk_u8_f32 v243, v98, 3, v99
	v_mfma_scale_f32_32x32x64_f8f6f4 v[2:17], v[220:227], v[244:251], v[2:17], v174, v174 op_sel_hi:[0,0,0] blgp:1
	ds_read_b128 v[130:133], v179 offset:28672
	ds_read_b128 v[134:137], v179 offset:29696
	ds_read_b128 v[180:183], v179 offset:30720
	ds_read_b128 v[184:187], v179 offset:31744
	ds_read_b128 v[188:191], v179 offset:32768
	ds_read_b128 v[192:195], v179 offset:33792
	ds_read_b128 v[196:199], v179 offset:34816
	ds_read_b128 v[200:203], v179 offset:35840
	ds_read_b128 v[220:223], v179 offset:36864
	ds_read_b128 v[224:227], v179 offset:37888
	ds_read_b128 v[228:231], v179 offset:38912
	ds_read_b128 v[232:235], v179 offset:39936
	s_waitcnt lgkmcnt(0)
	v_mfma_scale_f32_32x32x64_f8f6f4 v[130:145], v[130:137], v[146:153], v[50:65], v174, v174 op_sel_hi:[0,0,0]
	v_mfma_scale_f32_32x32x64_f8f6f4 v[114:129], v[180:187], v[146:153], v[50:65], v174, v174 op_sel_hi:[0,0,0]
	s_nop 15
	s_nop 2
	v_med3_f32 v109, v130, 0, v178
	v_med3_f32 v108, v131, 0, v178
	v_cvt_pk_u8_f32 v109, v109, 0, 0
	v_med3_f32 v110, v134, 0, v178
	v_med3_f32 v107, v132, 0, v178
	v_cvt_pk_u8_f32 v108, v108, 1, v109
	v_med3_f32 v109, v135, 0, v178
	v_cvt_pk_u8_f32 v110, v110, 0, 0
	v_med3_f32 v111, v138, 0, v178
	v_med3_f32 v106, v133, 0, v178
	v_cvt_pk_u8_f32 v107, v107, 2, v108
	v_med3_f32 v108, v136, 0, v178
	v_cvt_pk_u8_f32 v109, v109, 1, v110
	v_med3_f32 v110, v139, 0, v178
	v_cvt_pk_u8_f32 v111, v111, 0, 0
	v_mfma_scale_f32_16x16x128_f8f6f4 v[82:85], v[154:161], v[244:251], v[82:85], v174, v174 op_sel_hi:[0,0,0] blgp:1
	v_med3_f32 v112, v142, 0, v178
	v_cvt_pk_u8_f32 v106, v106, 3, v107
	v_med3_f32 v107, v137, 0, v178
	v_cvt_pk_u8_f32 v108, v108, 2, v109
	v_med3_f32 v109, v140, 0, v178
	v_cvt_pk_u8_f32 v110, v110, 1, v111
	v_med3_f32 v111, v143, 0, v178
	v_cvt_pk_u8_f32 v112, v112, 0, 0
	v_med3_f32 v113, v114, 0, v178
	v_cvt_pk_u8_f32 v107, v107, 3, v108
	v_med3_f32 v108, v141, 0, v178
	v_cvt_pk_u8_f32 v109, v109, 2, v110
	v_med3_f32 v110, v144, 0, v178
	v_cvt_pk_u8_f32 v111, v111, 1, v112
	v_med3_f32 v112, v115, 0, v178
	v_mfma_scale_f32_32x32x64_f8f6f4 v[66:81], v[188:195], v[236:243], v[66:81], v174, v174 op_sel_hi:[0,0,0] blgp:1
	v_cvt_pk_u8_f32 v113, v113, 0, 0
	v_med3_f32 v114, v118, 0, v178
	v_cvt_pk_u8_f32 v108, v108, 3, v109
	v_med3_f32 v109, v145, 0, v178
	v_cvt_pk_u8_f32 v110, v110, 2, v111
	v_med3_f32 v111, v116, 0, v178
	v_cvt_pk_u8_f32 v112, v112, 1, v113
	v_med3_f32 v113, v119, 0, v178
	v_cvt_pk_u8_f32 v114, v114, 0, 0
	v_med3_f32 v115, v122, 0, v178
	ds_read_b128 v[98:101], v179 offset:40960
	ds_read_b128 v[102:105], v179 offset:41984
	v_cvt_pk_u8_f32 v109, v109, 3, v110
	v_med3_f32 v110, v117, 0, v178
	v_cvt_pk_u8_f32 v111, v111, 2, v112
	v_med3_f32 v112, v120, 0, v178
	v_mfma_scale_f32_32x32x64_f8f6f4 v[34:49], v[196:203], v[236:243], v[34:49], v174, v174 op_sel_hi:[0,0,0] blgp:1
	v_cvt_pk_u8_f32 v113, v113, 1, v114
	v_med3_f32 v114, v123, 0, v178
	v_cvt_pk_u8_f32 v115, v115, 0, 0
	v_med3_f32 v116, v126, 0, v178
	v_cvt_pk_u8_f32 v110, v110, 3, v111
	v_med3_f32 v111, v121, 0, v178
	v_cvt_pk_u8_f32 v112, v112, 2, v113
	v_med3_f32 v113, v124, 0, v178
	v_cvt_pk_u8_f32 v114, v114, 1, v115
	v_med3_f32 v115, v127, 0, v178
	v_cvt_pk_u8_f32 v116, v116, 0, 0
	v_cvt_pk_u8_f32 v111, v111, 3, v112
	v_med3_f32 v112, v125, 0, v178
	v_cvt_pk_u8_f32 v113, v113, 2, v114
	v_med3_f32 v114, v128, 0, v178
	v_mfma_scale_f32_32x32x64_f8f6f4 v[18:33], v[220:227], v[236:243], v[18:33], v174, v174 op_sel_hi:[0,0,0] blgp:1
	v_cvt_pk_u8_f32 v115, v115, 1, v116
	v_cvt_pk_u8_f32 v112, v112, 3, v113
	v_med3_f32 v113, v129, 0, v178
	v_cvt_pk_u8_f32 v114, v114, 2, v115
	v_cvt_pk_u8_f32 v113, v113, 3, v114
	v_mfma_scale_f32_32x32x64_f8f6f4 v[2:17], v[228:235], v[236:243], v[2:17], v174, v174 op_sel_hi:[0,0,0] blgp:1
	v_mfma_scale_f32_16x16x128_f8f6f4 v[82:85], v[154:161], v[236:243], v[82:85], v174, v174 op_sel_hi:[0,0,0] blgp:1
	s_waitcnt lgkmcnt(0)
	v_mfma_scale_f32_32x32x64_f8f6f4 v[66:81], v[98:105], v[106:113], v[66:81], v174, v174 op_sel_hi:[0,0,0] blgp:1
	ds_read_b128 v[98:101], v179 offset:43008
	ds_read_b128 v[102:105], v179 offset:44032
	s_waitcnt lgkmcnt(0)
	v_mfma_scale_f32_32x32x64_f8f6f4 v[34:49], v[98:105], v[106:113], v[34:49], v174, v174 op_sel_hi:[0,0,0] blgp:1
	ds_read_b128 v[98:101], v179 offset:45056
	ds_read_b128 v[102:105], v179 offset:46080
	s_waitcnt lgkmcnt(0)
	v_mfma_scale_f32_32x32x64_f8f6f4 v[18:33], v[98:105], v[106:113], v[18:33], v174, v174 op_sel_hi:[0,0,0] blgp:1
	ds_read_b128 v[98:101], v179 offset:47104
	ds_read_b128 v[102:105], v179 offset:48128
	s_waitcnt lgkmcnt(0)
	v_mfma_scale_f32_32x32x64_f8f6f4 v[2:17], v[98:105], v[106:113], v[2:17], v174, v174 op_sel_hi:[0,0,0] blgp:1
	v_mfma_scale_f32_16x16x128_f8f6f4 v[82:85], v[154:161], v[106:113], v[82:85], v174, v174 op_sel_hi:[0,0,0] blgp:1
	s_cbranch_vccz .LBB0_4069
